# GEMM K-loops: LDS-DMA pieces per sub-phase 2/6/2/6 -> 2/4/4/6 (two A pieces moved one sub-phase later, waits tightened to keep the same guarantees)
# speedup vs baseline: 1.0091x; 1.0091x over previous
.Lpk0_LBB0_63:
.Lpk0_LBB0_64:
	s_add_u32 s4, s0, 0x100
	s_addc_u32 s5, s1, 0
	s_and_b64 s[56:57], s[6:7], exec
	s_cselect_b32 s8, 0, s4
	s_add_u32 s55, s31, s0
	s_addc_u32 s56, s53, s1
	s_and_b64 s[0:1], s[6:7], exec
	s_cselect_b32 s1, s21, s56
	s_cselect_b32 s0, s27, s55
	s_add_u32 s98, s2, s8
	s_addc_u32 s99, s3, s9
	s_mov_b32 m0, s35
	s_add_u32 s6, s0, 0x40000
	ds_read_b128 v[190:193], v180 offset:16384
	ds_read_b128 v[194:197], v180 offset:17408
	ds_read_b128 v[198:201], v180 offset:18432
	ds_read_b128 v[202:205], v180 offset:19456
	ds_read_b128 v[206:209], v180 offset:20480
	ds_read_b128 v[210:213], v180 offset:21504
	ds_read_b128 v[214:217], v180 offset:22528
	ds_read_b128 v[218:221], v180 offset:23552
	global_load_lds_dwordx4 v160, s[0:1]
	s_mov_b32 m0, s36
	s_addc_u32 s7, s1, 0
	global_load_lds_dwordx4 v162, s[0:1]
	s_mov_b32 m0, s37
	s_nop 0
	global_load_lds_dwordx4 v160, s[6:7]
	s_mov_b32 m0, s38
	s_nop 0
	global_load_lds_dwordx4 v162, s[6:7]
	s_waitcnt vmcnt(6)
	s_waitcnt lgkmcnt(0)
	s_barrier
	s_setprio 1
	s_waitcnt lgkmcnt(0)
	v_mfma_f32_16x16x32_bf16 v[60:63], v[144:147], v[190:193], 0
	v_mfma_f32_16x16x32_bf16 v[56:59], v[152:155], v[190:193], 0
	v_mfma_f32_16x16x32_bf16 v[44:47], v[144:147], v[198:201], 0
	v_mfma_f32_16x16x32_bf16 v[40:43], v[152:155], v[198:201], 0
	v_mfma_f32_16x16x32_bf16 v[28:31], v[144:147], v[206:209], 0
	v_mfma_f32_16x16x32_bf16 v[24:27], v[152:155], v[206:209], 0
	v_mfma_f32_16x16x32_bf16 v[12:15], v[144:147], v[214:217], 0
	v_mfma_f32_16x16x32_bf16 v[8:11], v[152:155], v[214:217], 0
	v_mfma_f32_16x16x32_bf16 v[60:63], v[148:151], v[194:197], v[60:63]
	v_mfma_f32_16x16x32_bf16 v[56:59], v[156:159], v[194:197], v[56:59]
	v_mfma_f32_16x16x32_bf16 v[44:47], v[148:151], v[202:205], v[44:47]
	v_mfma_f32_16x16x32_bf16 v[40:43], v[156:159], v[202:205], v[40:43]
	v_mfma_f32_16x16x32_bf16 v[28:31], v[148:151], v[210:213], v[28:31]
	v_mfma_f32_16x16x32_bf16 v[24:27], v[156:159], v[210:213], v[24:27]
	v_mfma_f32_16x16x32_bf16 v[12:15], v[148:151], v[218:221], v[12:15]
	v_mfma_f32_16x16x32_bf16 v[8:11], v[156:159], v[218:221], v[8:11]
	v_mfma_f32_16x16x32_bf16 v[52:55], v[128:131], v[190:193], 0
	v_mfma_f32_16x16x32_bf16 v[48:51], v[136:139], v[190:193], 0
	v_mfma_f32_16x16x32_bf16 v[36:39], v[128:131], v[198:201], 0
	v_mfma_f32_16x16x32_bf16 v[32:35], v[136:139], v[198:201], 0
	v_mfma_f32_16x16x32_bf16 v[20:23], v[128:131], v[206:209], 0
	v_mfma_f32_16x16x32_bf16 v[16:19], v[136:139], v[206:209], 0
	v_mfma_f32_16x16x32_bf16 v[4:7], v[128:131], v[214:217], 0
	v_mfma_f32_16x16x32_bf16 v[0:3], v[136:139], v[214:217], 0
	v_mfma_f32_16x16x32_bf16 v[52:55], v[132:135], v[194:197], v[52:55]
	v_mfma_f32_16x16x32_bf16 v[48:51], v[140:143], v[194:197], v[48:51]
	v_mfma_f32_16x16x32_bf16 v[36:39], v[132:135], v[202:205], v[36:39]
	v_mfma_f32_16x16x32_bf16 v[32:35], v[140:143], v[202:205], v[32:35]
	v_mfma_f32_16x16x32_bf16 v[20:23], v[132:135], v[210:213], v[20:23]
	v_mfma_f32_16x16x32_bf16 v[16:19], v[140:143], v[210:213], v[16:19]
	v_mfma_f32_16x16x32_bf16 v[4:7], v[132:135], v[218:221], v[4:7]
	v_mfma_f32_16x16x32_bf16 v[0:3], v[140:143], v[218:221], v[0:3]
	s_setprio 0
	s_barrier
	s_add_i32 s6, 0, 0x18000
	s_add_i32 s7, 0, 0x1c000
	v_add_u32_e32 v140, s6, v176
	v_add_u32_e32 v156, s7, v176
	ds_read_b128 v[128:131], v140
	ds_read_b128 v[132:135], v140 offset:1024
	ds_read_b128 v[136:139], v140 offset:2048
	ds_read_b128 v[140:143], v140 offset:3072
	ds_read_b128 v[144:147], v156
	ds_read_b128 v[148:151], v156 offset:1024
	ds_read_b128 v[152:155], v156 offset:2048
	ds_read_b128 v[156:159], v156 offset:3072
	s_mov_b32 m0, s40
	ds_read_b128 v[190:193], v180 offset:32768
	ds_read_b128 v[194:197], v180 offset:33792
	ds_read_b128 v[198:201], v180 offset:34816
	ds_read_b128 v[202:205], v180 offset:35840
	ds_read_b128 v[206:209], v180 offset:36864
	ds_read_b128 v[210:213], v180 offset:37888
	ds_read_b128 v[214:217], v180 offset:38912
	ds_read_b128 v[218:221], v180 offset:39936
	global_load_lds_dwordx4 v168, s[98:99]
	s_mov_b32 m0, s41
	s_nop 0
	global_load_lds_dwordx4 v170, s[98:99]
	s_mov_b32 m0, s34
	s_nop 0
	global_load_lds_dwordx4 v164, s[98:99]
	s_mov_b32 m0, s39
	s_nop 0
	global_load_lds_dwordx4 v166, s[98:99]
	s_waitcnt vmcnt(8)
	s_waitcnt lgkmcnt(0)
	s_barrier
	s_setprio 1
	s_waitcnt lgkmcnt(0)
	v_mfma_f32_16x16x32_bf16 v[124:127], v[128:131], v[190:193], v[124:127]
	v_mfma_f32_16x16x32_bf16 v[120:123], v[136:139], v[190:193], v[120:123]
	v_mfma_f32_16x16x32_bf16 v[108:111], v[128:131], v[198:201], v[108:111]
	v_mfma_f32_16x16x32_bf16 v[104:107], v[136:139], v[198:201], v[104:107]
	v_mfma_f32_16x16x32_bf16 v[92:95], v[128:131], v[206:209], v[92:95]
	v_mfma_f32_16x16x32_bf16 v[88:91], v[136:139], v[206:209], v[88:91]
	v_mfma_f32_16x16x32_bf16 v[76:79], v[128:131], v[214:217], v[76:79]
	v_mfma_f32_16x16x32_bf16 v[72:75], v[136:139], v[214:217], v[72:75]
	v_mfma_f32_16x16x32_bf16 v[124:127], v[132:135], v[194:197], v[124:127]
	v_mfma_f32_16x16x32_bf16 v[120:123], v[140:143], v[194:197], v[120:123]
	v_mfma_f32_16x16x32_bf16 v[108:111], v[132:135], v[202:205], v[108:111]
	v_mfma_f32_16x16x32_bf16 v[104:107], v[140:143], v[202:205], v[104:107]
	v_mfma_f32_16x16x32_bf16 v[92:95], v[132:135], v[210:213], v[92:95]
	v_mfma_f32_16x16x32_bf16 v[88:91], v[140:143], v[210:213], v[88:91]
	v_mfma_f32_16x16x32_bf16 v[76:79], v[132:135], v[218:221], v[76:79]
	v_mfma_f32_16x16x32_bf16 v[72:75], v[140:143], v[218:221], v[72:75]
	v_mfma_f32_16x16x32_bf16 v[116:119], v[144:147], v[190:193], v[116:119]
	v_mfma_f32_16x16x32_bf16 v[112:115], v[152:155], v[190:193], v[112:115]
	v_mfma_f32_16x16x32_bf16 v[100:103], v[144:147], v[198:201], v[100:103]
	v_mfma_f32_16x16x32_bf16 v[96:99], v[152:155], v[198:201], v[96:99]
	v_mfma_f32_16x16x32_bf16 v[84:87], v[144:147], v[206:209], v[84:87]
	v_mfma_f32_16x16x32_bf16 v[80:83], v[152:155], v[206:209], v[80:83]
	v_mfma_f32_16x16x32_bf16 v[68:71], v[144:147], v[214:217], v[68:71]
	v_mfma_f32_16x16x32_bf16 v[64:67], v[152:155], v[214:217], v[64:67]
	v_mfma_f32_16x16x32_bf16 v[116:119], v[148:151], v[194:197], v[116:119]
	v_mfma_f32_16x16x32_bf16 v[112:115], v[156:159], v[194:197], v[112:115]
	v_mfma_f32_16x16x32_bf16 v[100:103], v[148:151], v[202:205], v[100:103]
	v_mfma_f32_16x16x32_bf16 v[96:99], v[156:159], v[202:205], v[96:99]
	v_mfma_f32_16x16x32_bf16 v[84:87], v[148:151], v[210:213], v[84:87]
	v_mfma_f32_16x16x32_bf16 v[80:83], v[156:159], v[210:213], v[80:83]
	v_mfma_f32_16x16x32_bf16 v[68:71], v[148:151], v[218:221], v[68:71]
	v_mfma_f32_16x16x32_bf16 v[64:67], v[156:159], v[218:221], v[64:67]
	s_setprio 0
	s_barrier
	s_add_i32 s6, s6, s84
	s_add_u32 s100, s0, s14
	s_addc_u32 s101, s1, s15
	s_add_u32 s98, s98, s14
	s_addc_u32 s99, s99, s15
	s_mov_b32 m0, s6
	ds_read_b128 v[190:193], v180 offset:49152
	ds_read_b128 v[194:197], v180 offset:50176
	ds_read_b128 v[198:201], v180 offset:51200
	ds_read_b128 v[202:205], v180 offset:52224
	ds_read_b128 v[206:209], v180 offset:53248
	ds_read_b128 v[210:213], v180 offset:54272
	ds_read_b128 v[214:217], v180 offset:55296
	ds_read_b128 v[218:221], v180 offset:56320
	global_load_lds_dwordx4 v160, s[100:101]
	s_add_i32 m0, s6, 0x2000
	s_add_u32 s0, s0, 0x40080
	s_addc_u32 s1, s1, 0
	s_add_i32 s6, s7, s84
	global_load_lds_dwordx4 v162, s[100:101]
	s_mov_b32 m0, s6
	s_nop 0
	global_load_lds_dwordx4 v160, s[0:1]
	s_add_i32 m0, s6, 0x2000
	s_nop 0
	global_load_lds_dwordx4 v162, s[0:1]
	s_mov_b32 m0, s42
	s_nop 0
	global_load_lds_dwordx4 v164, s[98:99]
	s_mov_b32 m0, s43
	s_nop 0
	global_load_lds_dwordx4 v166, s[98:99]
	s_waitcnt vmcnt(6)
	s_waitcnt lgkmcnt(0)
	s_barrier
	s_setprio 1
	s_waitcnt lgkmcnt(0)
	v_mfma_f32_16x16x32_bf16 v[60:63], v[128:131], v[190:193], v[60:63]
	v_mfma_f32_16x16x32_bf16 v[56:59], v[136:139], v[190:193], v[56:59]
	v_mfma_f32_16x16x32_bf16 v[44:47], v[128:131], v[198:201], v[44:47]
	v_mfma_f32_16x16x32_bf16 v[40:43], v[136:139], v[198:201], v[40:43]
	v_mfma_f32_16x16x32_bf16 v[28:31], v[128:131], v[206:209], v[28:31]
	v_mfma_f32_16x16x32_bf16 v[24:27], v[136:139], v[206:209], v[24:27]
	v_mfma_f32_16x16x32_bf16 v[12:15], v[128:131], v[214:217], v[12:15]
	v_mfma_f32_16x16x32_bf16 v[8:11], v[136:139], v[214:217], v[8:11]
	v_mfma_f32_16x16x32_bf16 v[60:63], v[132:135], v[194:197], v[60:63]
	v_mfma_f32_16x16x32_bf16 v[56:59], v[140:143], v[194:197], v[56:59]
	v_mfma_f32_16x16x32_bf16 v[44:47], v[132:135], v[202:205], v[44:47]
	v_mfma_f32_16x16x32_bf16 v[40:43], v[140:143], v[202:205], v[40:43]
	v_mfma_f32_16x16x32_bf16 v[28:31], v[132:135], v[210:213], v[28:31]
	v_mfma_f32_16x16x32_bf16 v[24:27], v[140:143], v[210:213], v[24:27]
	v_mfma_f32_16x16x32_bf16 v[12:15], v[132:135], v[218:221], v[12:15]
	v_mfma_f32_16x16x32_bf16 v[8:11], v[140:143], v[218:221], v[8:11]
	v_mfma_f32_16x16x32_bf16 v[52:55], v[144:147], v[190:193], v[52:55]
	v_mfma_f32_16x16x32_bf16 v[48:51], v[152:155], v[190:193], v[48:51]
	v_mfma_f32_16x16x32_bf16 v[36:39], v[144:147], v[198:201], v[36:39]
	v_mfma_f32_16x16x32_bf16 v[32:35], v[152:155], v[198:201], v[32:35]
	v_mfma_f32_16x16x32_bf16 v[20:23], v[144:147], v[206:209], v[20:23]
	v_mfma_f32_16x16x32_bf16 v[16:19], v[152:155], v[206:209], v[16:19]
	v_mfma_f32_16x16x32_bf16 v[4:7], v[144:147], v[214:217], v[4:7]
	v_mfma_f32_16x16x32_bf16 v[0:3], v[152:155], v[214:217], v[0:3]
	v_mfma_f32_16x16x32_bf16 v[52:55], v[148:151], v[194:197], v[52:55]
	v_mfma_f32_16x16x32_bf16 v[48:51], v[156:159], v[194:197], v[48:51]
	v_mfma_f32_16x16x32_bf16 v[36:39], v[148:151], v[202:205], v[36:39]
	v_mfma_f32_16x16x32_bf16 v[32:35], v[156:159], v[202:205], v[32:35]
	v_mfma_f32_16x16x32_bf16 v[20:23], v[148:151], v[210:213], v[20:23]
	v_mfma_f32_16x16x32_bf16 v[16:19], v[156:159], v[210:213], v[16:19]
	v_mfma_f32_16x16x32_bf16 v[4:7], v[148:151], v[218:221], v[4:7]
	v_mfma_f32_16x16x32_bf16 v[0:3], v[156:159], v[218:221], v[0:3]
	s_setprio 0
	s_barrier
	s_add_i32 s54, s54, 2
	s_cmp_gt_u32 s54, 13
	s_cbranch_scc1 .LBB0_66
	s_mov_b64 s[0:1], s[4:5]
	s_branch .LBB0_61

.LBB0_63:
.LBB0_64:
	s_add_u32 s4, s0, 0x100
	s_addc_u32 s5, s1, 0
	s_and_b64 s[56:57], s[6:7], exec
	s_cselect_b32 s8, 0, s4
	s_add_u32 s55, s31, s0
	s_addc_u32 s56, s53, s1
	s_and_b64 s[0:1], s[6:7], exec
	s_cselect_b32 s1, s21, s56
	s_cselect_b32 s0, s27, s55
	s_add_u32 s98, s2, s8
	s_addc_u32 s99, s3, s9
	s_mov_b32 m0, s35
	s_add_u32 s6, s0, 0x40000
	ds_read_b128 v[190:193], v180 offset:16384
	ds_read_b128 v[194:197], v180 offset:17408
	ds_read_b128 v[198:201], v180 offset:18432
	ds_read_b128 v[202:205], v180 offset:19456
	ds_read_b128 v[206:209], v180 offset:20480
	ds_read_b128 v[210:213], v180 offset:21504
	ds_read_b128 v[214:217], v180 offset:22528
	ds_read_b128 v[218:221], v180 offset:23552
	global_load_lds_dwordx4 v160, s[0:1]
	s_mov_b32 m0, s36
	s_addc_u32 s7, s1, 0
	global_load_lds_dwordx4 v162, s[0:1]
	s_mov_b32 m0, s37
	s_nop 0
	global_load_lds_dwordx4 v160, s[6:7]
	s_mov_b32 m0, s38
	s_nop 0
	global_load_lds_dwordx4 v162, s[6:7]
	s_waitcnt vmcnt(6)
	s_waitcnt lgkmcnt(0)
	s_barrier
	s_setprio 1
	s_waitcnt lgkmcnt(0)
	v_mfma_f32_16x16x32_bf16 v[60:63], v[144:147], v[190:193], v[60:63]
	v_mfma_f32_16x16x32_bf16 v[56:59], v[152:155], v[190:193], v[56:59]
	v_mfma_f32_16x16x32_bf16 v[44:47], v[144:147], v[198:201], v[44:47]
	v_mfma_f32_16x16x32_bf16 v[40:43], v[152:155], v[198:201], v[40:43]
	v_mfma_f32_16x16x32_bf16 v[28:31], v[144:147], v[206:209], v[28:31]
	v_mfma_f32_16x16x32_bf16 v[24:27], v[152:155], v[206:209], v[24:27]
	v_mfma_f32_16x16x32_bf16 v[12:15], v[144:147], v[214:217], v[12:15]
	v_mfma_f32_16x16x32_bf16 v[8:11], v[152:155], v[214:217], v[8:11]
	v_mfma_f32_16x16x32_bf16 v[60:63], v[148:151], v[194:197], v[60:63]
	v_mfma_f32_16x16x32_bf16 v[56:59], v[156:159], v[194:197], v[56:59]
	v_mfma_f32_16x16x32_bf16 v[44:47], v[148:151], v[202:205], v[44:47]
	v_mfma_f32_16x16x32_bf16 v[40:43], v[156:159], v[202:205], v[40:43]
	v_mfma_f32_16x16x32_bf16 v[28:31], v[148:151], v[210:213], v[28:31]
	v_mfma_f32_16x16x32_bf16 v[24:27], v[156:159], v[210:213], v[24:27]
	v_mfma_f32_16x16x32_bf16 v[12:15], v[148:151], v[218:221], v[12:15]
	v_mfma_f32_16x16x32_bf16 v[8:11], v[156:159], v[218:221], v[8:11]
	v_mfma_f32_16x16x32_bf16 v[52:55], v[128:131], v[190:193], v[52:55]
	v_mfma_f32_16x16x32_bf16 v[48:51], v[136:139], v[190:193], v[48:51]
	v_mfma_f32_16x16x32_bf16 v[36:39], v[128:131], v[198:201], v[36:39]
	v_mfma_f32_16x16x32_bf16 v[32:35], v[136:139], v[198:201], v[32:35]
	v_mfma_f32_16x16x32_bf16 v[20:23], v[128:131], v[206:209], v[20:23]
	v_mfma_f32_16x16x32_bf16 v[16:19], v[136:139], v[206:209], v[16:19]
	v_mfma_f32_16x16x32_bf16 v[4:7], v[128:131], v[214:217], v[4:7]
	v_mfma_f32_16x16x32_bf16 v[0:3], v[136:139], v[214:217], v[0:3]
	v_mfma_f32_16x16x32_bf16 v[52:55], v[132:135], v[194:197], v[52:55]
	v_mfma_f32_16x16x32_bf16 v[48:51], v[140:143], v[194:197], v[48:51]
	v_mfma_f32_16x16x32_bf16 v[36:39], v[132:135], v[202:205], v[36:39]
	v_mfma_f32_16x16x32_bf16 v[32:35], v[140:143], v[202:205], v[32:35]
	v_mfma_f32_16x16x32_bf16 v[20:23], v[132:135], v[210:213], v[20:23]
	v_mfma_f32_16x16x32_bf16 v[16:19], v[140:143], v[210:213], v[16:19]
	v_mfma_f32_16x16x32_bf16 v[4:7], v[132:135], v[218:221], v[4:7]
	v_mfma_f32_16x16x32_bf16 v[0:3], v[140:143], v[218:221], v[0:3]
	s_setprio 0
	s_barrier
	s_add_i32 s6, 0, 0x18000
	s_add_i32 s7, 0, 0x1c000
	v_add_u32_e32 v140, s6, v176
	v_add_u32_e32 v156, s7, v176
	ds_read_b128 v[128:131], v140
	ds_read_b128 v[132:135], v140 offset:1024
	ds_read_b128 v[136:139], v140 offset:2048
	ds_read_b128 v[140:143], v140 offset:3072
	ds_read_b128 v[144:147], v156
	ds_read_b128 v[148:151], v156 offset:1024
	ds_read_b128 v[152:155], v156 offset:2048
	ds_read_b128 v[156:159], v156 offset:3072
	s_mov_b32 m0, s40
	ds_read_b128 v[190:193], v180 offset:32768
	ds_read_b128 v[194:197], v180 offset:33792
	ds_read_b128 v[198:201], v180 offset:34816
	ds_read_b128 v[202:205], v180 offset:35840
	ds_read_b128 v[206:209], v180 offset:36864
	ds_read_b128 v[210:213], v180 offset:37888
	ds_read_b128 v[214:217], v180 offset:38912
	ds_read_b128 v[218:221], v180 offset:39936
	global_load_lds_dwordx4 v168, s[98:99]
	s_mov_b32 m0, s41
	s_nop 0
	global_load_lds_dwordx4 v170, s[98:99]
	s_mov_b32 m0, s34
	s_nop 0
	global_load_lds_dwordx4 v164, s[98:99]
	s_mov_b32 m0, s39
	s_nop 0
	global_load_lds_dwordx4 v166, s[98:99]
	s_waitcnt vmcnt(8)
	s_waitcnt lgkmcnt(0)
	s_barrier
	s_setprio 1
	s_waitcnt lgkmcnt(0)
	v_mfma_f32_16x16x32_bf16 v[124:127], v[128:131], v[190:193], v[124:127]
	v_mfma_f32_16x16x32_bf16 v[120:123], v[136:139], v[190:193], v[120:123]
	v_mfma_f32_16x16x32_bf16 v[108:111], v[128:131], v[198:201], v[108:111]
	v_mfma_f32_16x16x32_bf16 v[104:107], v[136:139], v[198:201], v[104:107]
	v_mfma_f32_16x16x32_bf16 v[92:95], v[128:131], v[206:209], v[92:95]
	v_mfma_f32_16x16x32_bf16 v[88:91], v[136:139], v[206:209], v[88:91]
	v_mfma_f32_16x16x32_bf16 v[76:79], v[128:131], v[214:217], v[76:79]
	v_mfma_f32_16x16x32_bf16 v[72:75], v[136:139], v[214:217], v[72:75]
	v_mfma_f32_16x16x32_bf16 v[124:127], v[132:135], v[194:197], v[124:127]
	v_mfma_f32_16x16x32_bf16 v[120:123], v[140:143], v[194:197], v[120:123]
	v_mfma_f32_16x16x32_bf16 v[108:111], v[132:135], v[202:205], v[108:111]
	v_mfma_f32_16x16x32_bf16 v[104:107], v[140:143], v[202:205], v[104:107]
	v_mfma_f32_16x16x32_bf16 v[92:95], v[132:135], v[210:213], v[92:95]
	v_mfma_f32_16x16x32_bf16 v[88:91], v[140:143], v[210:213], v[88:91]
	v_mfma_f32_16x16x32_bf16 v[76:79], v[132:135], v[218:221], v[76:79]
	v_mfma_f32_16x16x32_bf16 v[72:75], v[140:143], v[218:221], v[72:75]
	v_mfma_f32_16x16x32_bf16 v[116:119], v[144:147], v[190:193], v[116:119]
	v_mfma_f32_16x16x32_bf16 v[112:115], v[152:155], v[190:193], v[112:115]
	v_mfma_f32_16x16x32_bf16 v[100:103], v[144:147], v[198:201], v[100:103]
	v_mfma_f32_16x16x32_bf16 v[96:99], v[152:155], v[198:201], v[96:99]
	v_mfma_f32_16x16x32_bf16 v[84:87], v[144:147], v[206:209], v[84:87]
	v_mfma_f32_16x16x32_bf16 v[80:83], v[152:155], v[206:209], v[80:83]
	v_mfma_f32_16x16x32_bf16 v[68:71], v[144:147], v[214:217], v[68:71]
	v_mfma_f32_16x16x32_bf16 v[64:67], v[152:155], v[214:217], v[64:67]
	v_mfma_f32_16x16x32_bf16 v[116:119], v[148:151], v[194:197], v[116:119]
	v_mfma_f32_16x16x32_bf16 v[112:115], v[156:159], v[194:197], v[112:115]
	v_mfma_f32_16x16x32_bf16 v[100:103], v[148:151], v[202:205], v[100:103]
	v_mfma_f32_16x16x32_bf16 v[96:99], v[156:159], v[202:205], v[96:99]
	v_mfma_f32_16x16x32_bf16 v[84:87], v[148:151], v[210:213], v[84:87]
	v_mfma_f32_16x16x32_bf16 v[80:83], v[156:159], v[210:213], v[80:83]
	v_mfma_f32_16x16x32_bf16 v[68:71], v[148:151], v[218:221], v[68:71]
	v_mfma_f32_16x16x32_bf16 v[64:67], v[156:159], v[218:221], v[64:67]
	s_setprio 0
	s_barrier
	s_add_i32 s6, s6, s84
	s_add_u32 s100, s0, s14
	s_addc_u32 s101, s1, s15
	s_add_u32 s98, s98, s14
	s_addc_u32 s99, s99, s15
	s_mov_b32 m0, s6
	ds_read_b128 v[190:193], v180 offset:49152
	ds_read_b128 v[194:197], v180 offset:50176
	ds_read_b128 v[198:201], v180 offset:51200
	ds_read_b128 v[202:205], v180 offset:52224
	ds_read_b128 v[206:209], v180 offset:53248
	ds_read_b128 v[210:213], v180 offset:54272
	ds_read_b128 v[214:217], v180 offset:55296
	ds_read_b128 v[218:221], v180 offset:56320
	global_load_lds_dwordx4 v160, s[100:101]
	s_add_i32 m0, s6, 0x2000
	s_add_u32 s0, s0, 0x40080
	s_addc_u32 s1, s1, 0
	s_add_i32 s6, s7, s84
	global_load_lds_dwordx4 v162, s[100:101]
	s_mov_b32 m0, s6
	s_nop 0
	global_load_lds_dwordx4 v160, s[0:1]
	s_add_i32 m0, s6, 0x2000
	s_nop 0
	global_load_lds_dwordx4 v162, s[0:1]
	s_mov_b32 m0, s42
	s_nop 0
	global_load_lds_dwordx4 v164, s[98:99]
	s_mov_b32 m0, s43
	s_nop 0
	global_load_lds_dwordx4 v166, s[98:99]
	s_waitcnt vmcnt(6)
	s_waitcnt lgkmcnt(0)
	s_barrier
	s_setprio 1
	s_waitcnt lgkmcnt(0)
	v_mfma_f32_16x16x32_bf16 v[60:63], v[128:131], v[190:193], v[60:63]
	v_mfma_f32_16x16x32_bf16 v[56:59], v[136:139], v[190:193], v[56:59]
	v_mfma_f32_16x16x32_bf16 v[44:47], v[128:131], v[198:201], v[44:47]
	v_mfma_f32_16x16x32_bf16 v[40:43], v[136:139], v[198:201], v[40:43]
	v_mfma_f32_16x16x32_bf16 v[28:31], v[128:131], v[206:209], v[28:31]
	v_mfma_f32_16x16x32_bf16 v[24:27], v[136:139], v[206:209], v[24:27]
	v_mfma_f32_16x16x32_bf16 v[12:15], v[128:131], v[214:217], v[12:15]
	v_mfma_f32_16x16x32_bf16 v[8:11], v[136:139], v[214:217], v[8:11]
	v_mfma_f32_16x16x32_bf16 v[60:63], v[132:135], v[194:197], v[60:63]
	v_mfma_f32_16x16x32_bf16 v[56:59], v[140:143], v[194:197], v[56:59]
	v_mfma_f32_16x16x32_bf16 v[44:47], v[132:135], v[202:205], v[44:47]
	v_mfma_f32_16x16x32_bf16 v[40:43], v[140:143], v[202:205], v[40:43]
	v_mfma_f32_16x16x32_bf16 v[28:31], v[132:135], v[210:213], v[28:31]
	v_mfma_f32_16x16x32_bf16 v[24:27], v[140:143], v[210:213], v[24:27]
	v_mfma_f32_16x16x32_bf16 v[12:15], v[132:135], v[218:221], v[12:15]
	v_mfma_f32_16x16x32_bf16 v[8:11], v[140:143], v[218:221], v[8:11]
	v_mfma_f32_16x16x32_bf16 v[52:55], v[144:147], v[190:193], v[52:55]
	v_mfma_f32_16x16x32_bf16 v[48:51], v[152:155], v[190:193], v[48:51]
	v_mfma_f32_16x16x32_bf16 v[36:39], v[144:147], v[198:201], v[36:39]
	v_mfma_f32_16x16x32_bf16 v[32:35], v[152:155], v[198:201], v[32:35]
	v_mfma_f32_16x16x32_bf16 v[20:23], v[144:147], v[206:209], v[20:23]
	v_mfma_f32_16x16x32_bf16 v[16:19], v[152:155], v[206:209], v[16:19]
	v_mfma_f32_16x16x32_bf16 v[4:7], v[144:147], v[214:217], v[4:7]
	v_mfma_f32_16x16x32_bf16 v[0:3], v[152:155], v[214:217], v[0:3]
	v_mfma_f32_16x16x32_bf16 v[52:55], v[148:151], v[194:197], v[52:55]
	v_mfma_f32_16x16x32_bf16 v[48:51], v[156:159], v[194:197], v[48:51]
	v_mfma_f32_16x16x32_bf16 v[36:39], v[148:151], v[202:205], v[36:39]
	v_mfma_f32_16x16x32_bf16 v[32:35], v[156:159], v[202:205], v[32:35]
	v_mfma_f32_16x16x32_bf16 v[20:23], v[148:151], v[210:213], v[20:23]
	v_mfma_f32_16x16x32_bf16 v[16:19], v[156:159], v[210:213], v[16:19]
	v_mfma_f32_16x16x32_bf16 v[4:7], v[148:151], v[218:221], v[4:7]
	v_mfma_f32_16x16x32_bf16 v[0:3], v[156:159], v[218:221], v[0:3]
	s_setprio 0
	s_barrier
	s_add_i32 s54, s54, 2
	s_cmp_gt_u32 s54, 13
	s_cbranch_scc1 .LBB0_66
	s_mov_b64 s[0:1], s[4:5]
	s_branch .LBB0_61

.Lpk1_LBB0_723:
.Lpk1_LBB0_724:
	s_add_u32 s22, s20, 0x100
	s_addc_u32 s23, s21, 0
	s_and_b64 s[52:53], s[24:25], exec
	s_cselect_b32 s0, 0, s22
	s_add_u32 s52, s49, s20
	s_addc_u32 s53, s50, s21
	s_and_b64 s[20:21], s[24:25], exec
	s_cselect_b32 s21, s15, s53
	s_cselect_b32 s20, s46, s52
	s_add_u32 s98, s2, s0
	s_addc_u32 s99, s3, s1
	s_mov_b32 m0, s28
	s_add_u32 s24, s20, 0x40000
	ds_read_b128 v[180:183], v179 offset:16384
	ds_read_b128 v[184:187], v179 offset:17408
	ds_read_b128 v[188:191], v179 offset:18432
	ds_read_b128 v[192:195], v179 offset:19456
	ds_read_b128 v[196:199], v179 offset:20480
	ds_read_b128 v[200:203], v179 offset:21504
	ds_read_b128 v[204:207], v179 offset:22528
	ds_read_b128 v[208:211], v179 offset:23552
	global_load_lds_dwordx4 v162, s[20:21]
	s_mov_b32 m0, s29
	s_addc_u32 s25, s21, 0
	global_load_lds_dwordx4 v160, s[20:21]
	s_mov_b32 m0, s30
	s_nop 0
	global_load_lds_dwordx4 v162, s[24:25]
	s_mov_b32 m0, s31
	s_nop 0
	global_load_lds_dwordx4 v160, s[24:25]
	s_waitcnt vmcnt(6)
	s_waitcnt lgkmcnt(0)
	s_barrier
	s_setprio 1
	s_waitcnt lgkmcnt(0)
	v_mfma_f32_16x16x32_bf16 v[60:63], v[144:147], v[180:183], 0
	v_mfma_f32_16x16x32_bf16 v[56:59], v[152:155], v[180:183], 0
	v_mfma_f32_16x16x32_bf16 v[48:51], v[144:147], v[188:191], 0
	v_mfma_f32_16x16x32_bf16 v[40:43], v[152:155], v[188:191], 0
	v_mfma_f32_16x16x32_bf16 v[32:35], v[144:147], v[196:199], 0
	v_mfma_f32_16x16x32_bf16 v[24:27], v[152:155], v[196:199], 0
	v_mfma_f32_16x16x32_bf16 v[16:19], v[144:147], v[204:207], 0
	v_mfma_f32_16x16x32_bf16 v[8:11], v[152:155], v[204:207], 0
	v_mfma_f32_16x16x32_bf16 v[60:63], v[148:151], v[184:187], v[60:63]
	v_mfma_f32_16x16x32_bf16 v[56:59], v[156:159], v[184:187], v[56:59]
	v_mfma_f32_16x16x32_bf16 v[48:51], v[148:151], v[192:195], v[48:51]
	v_mfma_f32_16x16x32_bf16 v[40:43], v[156:159], v[192:195], v[40:43]
	v_mfma_f32_16x16x32_bf16 v[32:35], v[148:151], v[200:203], v[32:35]
	v_mfma_f32_16x16x32_bf16 v[24:27], v[156:159], v[200:203], v[24:27]
	v_mfma_f32_16x16x32_bf16 v[16:19], v[148:151], v[208:211], v[16:19]
	v_mfma_f32_16x16x32_bf16 v[8:11], v[156:159], v[208:211], v[8:11]
	v_mfma_f32_16x16x32_bf16 v[52:55], v[128:131], v[180:183], 0
	v_mfma_f32_16x16x32_bf16 v[44:47], v[136:139], v[180:183], 0
	v_mfma_f32_16x16x32_bf16 v[36:39], v[128:131], v[188:191], 0
	v_mfma_f32_16x16x32_bf16 v[28:31], v[136:139], v[188:191], 0
	v_mfma_f32_16x16x32_bf16 v[20:23], v[128:131], v[196:199], 0
	v_mfma_f32_16x16x32_bf16 v[12:15], v[136:139], v[196:199], 0
	v_mfma_f32_16x16x32_bf16 v[4:7], v[128:131], v[204:207], 0
	v_mfma_f32_16x16x32_bf16 v[0:3], v[136:139], v[204:207], 0
	v_mfma_f32_16x16x32_bf16 v[52:55], v[132:135], v[184:187], v[52:55]
	v_mfma_f32_16x16x32_bf16 v[44:47], v[140:143], v[184:187], v[44:47]
	v_mfma_f32_16x16x32_bf16 v[36:39], v[132:135], v[192:195], v[36:39]
	v_mfma_f32_16x16x32_bf16 v[28:31], v[140:143], v[192:195], v[28:31]
	v_mfma_f32_16x16x32_bf16 v[20:23], v[132:135], v[200:203], v[20:23]
	v_mfma_f32_16x16x32_bf16 v[12:15], v[140:143], v[200:203], v[12:15]
	v_mfma_f32_16x16x32_bf16 v[4:7], v[132:135], v[208:211], v[4:7]
	v_mfma_f32_16x16x32_bf16 v[0:3], v[140:143], v[208:211], v[0:3]
	s_setprio 0
	s_barrier
	s_add_i32 s24, 0, 0x18000
	s_add_i32 s25, 0, 0x1c000
	v_add_u32_e32 v140, s24, v176
	v_add_u32_e32 v156, s25, v176
	ds_read_b128 v[128:131], v140
	ds_read_b128 v[132:135], v140 offset:1024
	ds_read_b128 v[136:139], v140 offset:2048
	ds_read_b128 v[140:143], v140 offset:3072
	ds_read_b128 v[144:147], v156
	ds_read_b128 v[148:151], v156 offset:1024
	ds_read_b128 v[152:155], v156 offset:2048
	ds_read_b128 v[156:159], v156 offset:3072
	s_mov_b32 m0, s35
	ds_read_b128 v[180:183], v179 offset:32768
	ds_read_b128 v[184:187], v179 offset:33792
	ds_read_b128 v[188:191], v179 offset:34816
	ds_read_b128 v[192:195], v179 offset:35840
	ds_read_b128 v[196:199], v179 offset:36864
	ds_read_b128 v[200:203], v179 offset:37888
	ds_read_b128 v[204:207], v179 offset:38912
	ds_read_b128 v[208:211], v179 offset:39936
	global_load_lds_dwordx4 v168, s[98:99]
	s_mov_b32 m0, s36
	s_nop 0
	global_load_lds_dwordx4 v170, s[98:99]
	s_mov_b32 m0, s27
	s_nop 0
	global_load_lds_dwordx4 v164, s[98:99]
	s_mov_b32 m0, s34
	s_nop 0
	global_load_lds_dwordx4 v166, s[98:99]
	s_waitcnt vmcnt(8)
	s_waitcnt lgkmcnt(0)
	s_barrier
	s_setprio 1
	s_waitcnt lgkmcnt(0)
	v_mfma_f32_16x16x32_bf16 v[124:127], v[128:131], v[180:183], v[124:127]
	v_mfma_f32_16x16x32_bf16 v[120:123], v[136:139], v[180:183], v[120:123]
	v_mfma_f32_16x16x32_bf16 v[112:115], v[128:131], v[188:191], v[112:115]
	v_mfma_f32_16x16x32_bf16 v[104:107], v[136:139], v[188:191], v[104:107]
	v_mfma_f32_16x16x32_bf16 v[96:99], v[128:131], v[196:199], v[96:99]
	v_mfma_f32_16x16x32_bf16 v[88:91], v[136:139], v[196:199], v[88:91]
	v_mfma_f32_16x16x32_bf16 v[80:83], v[128:131], v[204:207], v[80:83]
	v_mfma_f32_16x16x32_bf16 v[72:75], v[136:139], v[204:207], v[72:75]
	v_mfma_f32_16x16x32_bf16 v[124:127], v[132:135], v[184:187], v[124:127]
	v_mfma_f32_16x16x32_bf16 v[120:123], v[140:143], v[184:187], v[120:123]
	v_mfma_f32_16x16x32_bf16 v[112:115], v[132:135], v[192:195], v[112:115]
	v_mfma_f32_16x16x32_bf16 v[104:107], v[140:143], v[192:195], v[104:107]
	v_mfma_f32_16x16x32_bf16 v[96:99], v[132:135], v[200:203], v[96:99]
	v_mfma_f32_16x16x32_bf16 v[88:91], v[140:143], v[200:203], v[88:91]
	v_mfma_f32_16x16x32_bf16 v[80:83], v[132:135], v[208:211], v[80:83]
	v_mfma_f32_16x16x32_bf16 v[72:75], v[140:143], v[208:211], v[72:75]
	v_mfma_f32_16x16x32_bf16 v[116:119], v[144:147], v[180:183], v[116:119]
	v_mfma_f32_16x16x32_bf16 v[108:111], v[152:155], v[180:183], v[108:111]
	v_mfma_f32_16x16x32_bf16 v[100:103], v[144:147], v[188:191], v[100:103]
	v_mfma_f32_16x16x32_bf16 v[92:95], v[152:155], v[188:191], v[92:95]
	v_mfma_f32_16x16x32_bf16 v[84:87], v[144:147], v[196:199], v[84:87]
	v_mfma_f32_16x16x32_bf16 v[76:79], v[152:155], v[196:199], v[76:79]
	v_mfma_f32_16x16x32_bf16 v[68:71], v[144:147], v[204:207], v[68:71]
	v_mfma_f32_16x16x32_bf16 v[64:67], v[152:155], v[204:207], v[64:67]
	v_mfma_f32_16x16x32_bf16 v[116:119], v[148:151], v[184:187], v[116:119]
	v_mfma_f32_16x16x32_bf16 v[108:111], v[156:159], v[184:187], v[108:111]
	v_mfma_f32_16x16x32_bf16 v[100:103], v[148:151], v[192:195], v[100:103]
	v_mfma_f32_16x16x32_bf16 v[92:95], v[156:159], v[192:195], v[92:95]
	v_mfma_f32_16x16x32_bf16 v[84:87], v[148:151], v[200:203], v[84:87]
	v_mfma_f32_16x16x32_bf16 v[76:79], v[156:159], v[200:203], v[76:79]
	v_mfma_f32_16x16x32_bf16 v[68:71], v[148:151], v[208:211], v[68:71]
	v_mfma_f32_16x16x32_bf16 v[64:67], v[156:159], v[208:211], v[64:67]
	s_setprio 0
	s_barrier
	s_add_i32 s0, s24, s84
	s_add_u32 s100, s20, s6
	s_addc_u32 s101, s21, s7
	s_add_u32 s98, s98, s6
	s_addc_u32 s99, s99, s7
	s_mov_b32 m0, s0
	ds_read_b128 v[180:183], v179 offset:49152
	ds_read_b128 v[184:187], v179 offset:50176
	ds_read_b128 v[188:191], v179 offset:51200
	ds_read_b128 v[192:195], v179 offset:52224
	ds_read_b128 v[196:199], v179 offset:53248
	ds_read_b128 v[200:203], v179 offset:54272
	ds_read_b128 v[204:207], v179 offset:55296
	ds_read_b128 v[208:211], v179 offset:56320
	global_load_lds_dwordx4 v162, s[100:101]
	s_add_i32 m0, s0, 0x2000
	s_add_u32 s20, s20, 0x40080
	s_addc_u32 s21, s21, 0
	s_add_i32 s0, s25, s84
	global_load_lds_dwordx4 v160, s[100:101]
	s_mov_b32 m0, s0
	s_nop 0
	global_load_lds_dwordx4 v162, s[20:21]
	s_add_i32 m0, s0, 0x2000
	s_nop 0
	global_load_lds_dwordx4 v160, s[20:21]
	s_mov_b32 m0, s37
	s_nop 0
	global_load_lds_dwordx4 v164, s[98:99]
	s_mov_b32 m0, s38
	s_nop 0
	global_load_lds_dwordx4 v166, s[98:99]
	s_waitcnt vmcnt(6)
	s_waitcnt lgkmcnt(0)
	s_barrier
	s_setprio 1
	s_waitcnt lgkmcnt(0)
	v_mfma_f32_16x16x32_bf16 v[60:63], v[128:131], v[180:183], v[60:63]
	v_mfma_f32_16x16x32_bf16 v[56:59], v[136:139], v[180:183], v[56:59]
	v_mfma_f32_16x16x32_bf16 v[48:51], v[128:131], v[188:191], v[48:51]
	v_mfma_f32_16x16x32_bf16 v[40:43], v[136:139], v[188:191], v[40:43]
	v_mfma_f32_16x16x32_bf16 v[32:35], v[128:131], v[196:199], v[32:35]
	v_mfma_f32_16x16x32_bf16 v[24:27], v[136:139], v[196:199], v[24:27]
	v_mfma_f32_16x16x32_bf16 v[16:19], v[128:131], v[204:207], v[16:19]
	v_mfma_f32_16x16x32_bf16 v[8:11], v[136:139], v[204:207], v[8:11]
	v_mfma_f32_16x16x32_bf16 v[60:63], v[132:135], v[184:187], v[60:63]
	v_mfma_f32_16x16x32_bf16 v[56:59], v[140:143], v[184:187], v[56:59]
	v_mfma_f32_16x16x32_bf16 v[48:51], v[132:135], v[192:195], v[48:51]
	v_mfma_f32_16x16x32_bf16 v[40:43], v[140:143], v[192:195], v[40:43]
	v_mfma_f32_16x16x32_bf16 v[32:35], v[132:135], v[200:203], v[32:35]
	v_mfma_f32_16x16x32_bf16 v[24:27], v[140:143], v[200:203], v[24:27]
	v_mfma_f32_16x16x32_bf16 v[16:19], v[132:135], v[208:211], v[16:19]
	v_mfma_f32_16x16x32_bf16 v[8:11], v[140:143], v[208:211], v[8:11]
	v_mfma_f32_16x16x32_bf16 v[52:55], v[144:147], v[180:183], v[52:55]
	v_mfma_f32_16x16x32_bf16 v[44:47], v[152:155], v[180:183], v[44:47]
	v_mfma_f32_16x16x32_bf16 v[36:39], v[144:147], v[188:191], v[36:39]
	v_mfma_f32_16x16x32_bf16 v[28:31], v[152:155], v[188:191], v[28:31]
	v_mfma_f32_16x16x32_bf16 v[20:23], v[144:147], v[196:199], v[20:23]
	v_mfma_f32_16x16x32_bf16 v[12:15], v[152:155], v[196:199], v[12:15]
	v_mfma_f32_16x16x32_bf16 v[4:7], v[144:147], v[204:207], v[4:7]
	v_mfma_f32_16x16x32_bf16 v[0:3], v[152:155], v[204:207], v[0:3]
	v_mfma_f32_16x16x32_bf16 v[52:55], v[148:151], v[184:187], v[52:55]
	v_mfma_f32_16x16x32_bf16 v[44:47], v[156:159], v[184:187], v[44:47]
	v_mfma_f32_16x16x32_bf16 v[36:39], v[148:151], v[192:195], v[36:39]
	v_mfma_f32_16x16x32_bf16 v[28:31], v[156:159], v[192:195], v[28:31]
	v_mfma_f32_16x16x32_bf16 v[20:23], v[148:151], v[200:203], v[20:23]
	v_mfma_f32_16x16x32_bf16 v[12:15], v[156:159], v[200:203], v[12:15]
	v_mfma_f32_16x16x32_bf16 v[4:7], v[148:151], v[208:211], v[4:7]
	v_mfma_f32_16x16x32_bf16 v[0:3], v[156:159], v[208:211], v[0:3]
	s_setprio 0
	s_barrier
	s_add_i32 s51, s51, 2
	s_cmp_gt_u32 s51, 13
	s_cbranch_scc1 .LBB0_726
	s_mov_b64 s[20:21], s[22:23]
	s_branch .LBB0_721

.LBB0_723:
.LBB0_724:
	s_add_u32 s22, s20, 0x100
	s_addc_u32 s23, s21, 0
	s_and_b64 s[52:53], s[24:25], exec
	s_cselect_b32 s0, 0, s22
	s_add_u32 s52, s49, s20
	s_addc_u32 s53, s50, s21
	s_and_b64 s[20:21], s[24:25], exec
	s_cselect_b32 s21, s15, s53
	s_cselect_b32 s20, s46, s52
	s_add_u32 s98, s2, s0
	s_addc_u32 s99, s3, s1
	s_mov_b32 m0, s28
	s_add_u32 s24, s20, 0x40000
	ds_read_b128 v[180:183], v179 offset:16384
	ds_read_b128 v[184:187], v179 offset:17408
	ds_read_b128 v[188:191], v179 offset:18432
	ds_read_b128 v[192:195], v179 offset:19456
	ds_read_b128 v[196:199], v179 offset:20480
	ds_read_b128 v[200:203], v179 offset:21504
	ds_read_b128 v[204:207], v179 offset:22528
	ds_read_b128 v[208:211], v179 offset:23552
	global_load_lds_dwordx4 v162, s[20:21]
	s_mov_b32 m0, s29
	s_addc_u32 s25, s21, 0
	global_load_lds_dwordx4 v160, s[20:21]
	s_mov_b32 m0, s30
	s_nop 0
	global_load_lds_dwordx4 v162, s[24:25]
	s_mov_b32 m0, s31
	s_nop 0
	global_load_lds_dwordx4 v160, s[24:25]
	s_waitcnt vmcnt(6)
	s_waitcnt lgkmcnt(0)
	s_barrier
	s_setprio 1
	s_waitcnt lgkmcnt(0)
	v_mfma_f32_16x16x32_bf16 v[60:63], v[144:147], v[180:183], v[60:63]
	v_mfma_f32_16x16x32_bf16 v[56:59], v[152:155], v[180:183], v[56:59]
	v_mfma_f32_16x16x32_bf16 v[48:51], v[144:147], v[188:191], v[48:51]
	v_mfma_f32_16x16x32_bf16 v[40:43], v[152:155], v[188:191], v[40:43]
	v_mfma_f32_16x16x32_bf16 v[32:35], v[144:147], v[196:199], v[32:35]
	v_mfma_f32_16x16x32_bf16 v[24:27], v[152:155], v[196:199], v[24:27]
	v_mfma_f32_16x16x32_bf16 v[16:19], v[144:147], v[204:207], v[16:19]
	v_mfma_f32_16x16x32_bf16 v[8:11], v[152:155], v[204:207], v[8:11]
	v_mfma_f32_16x16x32_bf16 v[60:63], v[148:151], v[184:187], v[60:63]
	v_mfma_f32_16x16x32_bf16 v[56:59], v[156:159], v[184:187], v[56:59]
	v_mfma_f32_16x16x32_bf16 v[48:51], v[148:151], v[192:195], v[48:51]
	v_mfma_f32_16x16x32_bf16 v[40:43], v[156:159], v[192:195], v[40:43]
	v_mfma_f32_16x16x32_bf16 v[32:35], v[148:151], v[200:203], v[32:35]
	v_mfma_f32_16x16x32_bf16 v[24:27], v[156:159], v[200:203], v[24:27]
	v_mfma_f32_16x16x32_bf16 v[16:19], v[148:151], v[208:211], v[16:19]
	v_mfma_f32_16x16x32_bf16 v[8:11], v[156:159], v[208:211], v[8:11]
	v_mfma_f32_16x16x32_bf16 v[52:55], v[128:131], v[180:183], v[52:55]
	v_mfma_f32_16x16x32_bf16 v[44:47], v[136:139], v[180:183], v[44:47]
	v_mfma_f32_16x16x32_bf16 v[36:39], v[128:131], v[188:191], v[36:39]
	v_mfma_f32_16x16x32_bf16 v[28:31], v[136:139], v[188:191], v[28:31]
	v_mfma_f32_16x16x32_bf16 v[20:23], v[128:131], v[196:199], v[20:23]
	v_mfma_f32_16x16x32_bf16 v[12:15], v[136:139], v[196:199], v[12:15]
	v_mfma_f32_16x16x32_bf16 v[4:7], v[128:131], v[204:207], v[4:7]
	v_mfma_f32_16x16x32_bf16 v[0:3], v[136:139], v[204:207], v[0:3]
	v_mfma_f32_16x16x32_bf16 v[52:55], v[132:135], v[184:187], v[52:55]
	v_mfma_f32_16x16x32_bf16 v[44:47], v[140:143], v[184:187], v[44:47]
	v_mfma_f32_16x16x32_bf16 v[36:39], v[132:135], v[192:195], v[36:39]
	v_mfma_f32_16x16x32_bf16 v[28:31], v[140:143], v[192:195], v[28:31]
	v_mfma_f32_16x16x32_bf16 v[20:23], v[132:135], v[200:203], v[20:23]
	v_mfma_f32_16x16x32_bf16 v[12:15], v[140:143], v[200:203], v[12:15]
	v_mfma_f32_16x16x32_bf16 v[4:7], v[132:135], v[208:211], v[4:7]
	v_mfma_f32_16x16x32_bf16 v[0:3], v[140:143], v[208:211], v[0:3]
	s_setprio 0
	s_barrier
	s_add_i32 s24, 0, 0x18000
	s_add_i32 s25, 0, 0x1c000
	v_add_u32_e32 v140, s24, v176
	v_add_u32_e32 v156, s25, v176
	ds_read_b128 v[128:131], v140
	ds_read_b128 v[132:135], v140 offset:1024
	ds_read_b128 v[136:139], v140 offset:2048
	ds_read_b128 v[140:143], v140 offset:3072
	ds_read_b128 v[144:147], v156
	ds_read_b128 v[148:151], v156 offset:1024
	ds_read_b128 v[152:155], v156 offset:2048
	ds_read_b128 v[156:159], v156 offset:3072
	s_mov_b32 m0, s35
	ds_read_b128 v[180:183], v179 offset:32768
	ds_read_b128 v[184:187], v179 offset:33792
	ds_read_b128 v[188:191], v179 offset:34816
	ds_read_b128 v[192:195], v179 offset:35840
	ds_read_b128 v[196:199], v179 offset:36864
	ds_read_b128 v[200:203], v179 offset:37888
	ds_read_b128 v[204:207], v179 offset:38912
	ds_read_b128 v[208:211], v179 offset:39936
	global_load_lds_dwordx4 v168, s[98:99]
	s_mov_b32 m0, s36
	s_nop 0
	global_load_lds_dwordx4 v170, s[98:99]
	s_mov_b32 m0, s27
	s_nop 0
	global_load_lds_dwordx4 v164, s[98:99]
	s_mov_b32 m0, s34
	s_nop 0
	global_load_lds_dwordx4 v166, s[98:99]
	s_waitcnt vmcnt(8)
	s_waitcnt lgkmcnt(0)
	s_barrier
	s_setprio 1
	s_waitcnt lgkmcnt(0)
	v_mfma_f32_16x16x32_bf16 v[124:127], v[128:131], v[180:183], v[124:127]
	v_mfma_f32_16x16x32_bf16 v[120:123], v[136:139], v[180:183], v[120:123]
	v_mfma_f32_16x16x32_bf16 v[112:115], v[128:131], v[188:191], v[112:115]
	v_mfma_f32_16x16x32_bf16 v[104:107], v[136:139], v[188:191], v[104:107]
	v_mfma_f32_16x16x32_bf16 v[96:99], v[128:131], v[196:199], v[96:99]
	v_mfma_f32_16x16x32_bf16 v[88:91], v[136:139], v[196:199], v[88:91]
	v_mfma_f32_16x16x32_bf16 v[80:83], v[128:131], v[204:207], v[80:83]
	v_mfma_f32_16x16x32_bf16 v[72:75], v[136:139], v[204:207], v[72:75]
	v_mfma_f32_16x16x32_bf16 v[124:127], v[132:135], v[184:187], v[124:127]
	v_mfma_f32_16x16x32_bf16 v[120:123], v[140:143], v[184:187], v[120:123]
	v_mfma_f32_16x16x32_bf16 v[112:115], v[132:135], v[192:195], v[112:115]
	v_mfma_f32_16x16x32_bf16 v[104:107], v[140:143], v[192:195], v[104:107]
	v_mfma_f32_16x16x32_bf16 v[96:99], v[132:135], v[200:203], v[96:99]
	v_mfma_f32_16x16x32_bf16 v[88:91], v[140:143], v[200:203], v[88:91]
	v_mfma_f32_16x16x32_bf16 v[80:83], v[132:135], v[208:211], v[80:83]
	v_mfma_f32_16x16x32_bf16 v[72:75], v[140:143], v[208:211], v[72:75]
	v_mfma_f32_16x16x32_bf16 v[116:119], v[144:147], v[180:183], v[116:119]
	v_mfma_f32_16x16x32_bf16 v[108:111], v[152:155], v[180:183], v[108:111]
	v_mfma_f32_16x16x32_bf16 v[100:103], v[144:147], v[188:191], v[100:103]
	v_mfma_f32_16x16x32_bf16 v[92:95], v[152:155], v[188:191], v[92:95]
	v_mfma_f32_16x16x32_bf16 v[84:87], v[144:147], v[196:199], v[84:87]
	v_mfma_f32_16x16x32_bf16 v[76:79], v[152:155], v[196:199], v[76:79]
	v_mfma_f32_16x16x32_bf16 v[68:71], v[144:147], v[204:207], v[68:71]
	v_mfma_f32_16x16x32_bf16 v[64:67], v[152:155], v[204:207], v[64:67]
	v_mfma_f32_16x16x32_bf16 v[116:119], v[148:151], v[184:187], v[116:119]
	v_mfma_f32_16x16x32_bf16 v[108:111], v[156:159], v[184:187], v[108:111]
	v_mfma_f32_16x16x32_bf16 v[100:103], v[148:151], v[192:195], v[100:103]
	v_mfma_f32_16x16x32_bf16 v[92:95], v[156:159], v[192:195], v[92:95]
	v_mfma_f32_16x16x32_bf16 v[84:87], v[148:151], v[200:203], v[84:87]
	v_mfma_f32_16x16x32_bf16 v[76:79], v[156:159], v[200:203], v[76:79]
	v_mfma_f32_16x16x32_bf16 v[68:71], v[148:151], v[208:211], v[68:71]
	v_mfma_f32_16x16x32_bf16 v[64:67], v[156:159], v[208:211], v[64:67]
	s_setprio 0
	s_barrier
	s_add_i32 s0, s24, s84
	s_add_u32 s100, s20, s6
	s_addc_u32 s101, s21, s7
	s_add_u32 s98, s98, s6
	s_addc_u32 s99, s99, s7
	s_mov_b32 m0, s0
	ds_read_b128 v[180:183], v179 offset:49152
	ds_read_b128 v[184:187], v179 offset:50176
	ds_read_b128 v[188:191], v179 offset:51200
	ds_read_b128 v[192:195], v179 offset:52224
	ds_read_b128 v[196:199], v179 offset:53248
	ds_read_b128 v[200:203], v179 offset:54272
	ds_read_b128 v[204:207], v179 offset:55296
	ds_read_b128 v[208:211], v179 offset:56320
	global_load_lds_dwordx4 v162, s[100:101]
	s_add_i32 m0, s0, 0x2000
	s_add_u32 s20, s20, 0x40080
	s_addc_u32 s21, s21, 0
	s_add_i32 s0, s25, s84
	global_load_lds_dwordx4 v160, s[100:101]
	s_mov_b32 m0, s0
	s_nop 0
	global_load_lds_dwordx4 v162, s[20:21]
	s_add_i32 m0, s0, 0x2000
	s_nop 0
	global_load_lds_dwordx4 v160, s[20:21]
	s_mov_b32 m0, s37
	s_nop 0
	global_load_lds_dwordx4 v164, s[98:99]
	s_mov_b32 m0, s38
	s_nop 0
	global_load_lds_dwordx4 v166, s[98:99]
	s_waitcnt vmcnt(6)
	s_waitcnt lgkmcnt(0)
	s_barrier
	s_setprio 1
	s_waitcnt lgkmcnt(0)
	v_mfma_f32_16x16x32_bf16 v[60:63], v[128:131], v[180:183], v[60:63]
	v_mfma_f32_16x16x32_bf16 v[56:59], v[136:139], v[180:183], v[56:59]
	v_mfma_f32_16x16x32_bf16 v[48:51], v[128:131], v[188:191], v[48:51]
	v_mfma_f32_16x16x32_bf16 v[40:43], v[136:139], v[188:191], v[40:43]
	v_mfma_f32_16x16x32_bf16 v[32:35], v[128:131], v[196:199], v[32:35]
	v_mfma_f32_16x16x32_bf16 v[24:27], v[136:139], v[196:199], v[24:27]
	v_mfma_f32_16x16x32_bf16 v[16:19], v[128:131], v[204:207], v[16:19]
	v_mfma_f32_16x16x32_bf16 v[8:11], v[136:139], v[204:207], v[8:11]
	v_mfma_f32_16x16x32_bf16 v[60:63], v[132:135], v[184:187], v[60:63]
	v_mfma_f32_16x16x32_bf16 v[56:59], v[140:143], v[184:187], v[56:59]
	v_mfma_f32_16x16x32_bf16 v[48:51], v[132:135], v[192:195], v[48:51]
	v_mfma_f32_16x16x32_bf16 v[40:43], v[140:143], v[192:195], v[40:43]
	v_mfma_f32_16x16x32_bf16 v[32:35], v[132:135], v[200:203], v[32:35]
	v_mfma_f32_16x16x32_bf16 v[24:27], v[140:143], v[200:203], v[24:27]
	v_mfma_f32_16x16x32_bf16 v[16:19], v[132:135], v[208:211], v[16:19]
	v_mfma_f32_16x16x32_bf16 v[8:11], v[140:143], v[208:211], v[8:11]
	v_mfma_f32_16x16x32_bf16 v[52:55], v[144:147], v[180:183], v[52:55]
	v_mfma_f32_16x16x32_bf16 v[44:47], v[152:155], v[180:183], v[44:47]
	v_mfma_f32_16x16x32_bf16 v[36:39], v[144:147], v[188:191], v[36:39]
	v_mfma_f32_16x16x32_bf16 v[28:31], v[152:155], v[188:191], v[28:31]
	v_mfma_f32_16x16x32_bf16 v[20:23], v[144:147], v[196:199], v[20:23]
	v_mfma_f32_16x16x32_bf16 v[12:15], v[152:155], v[196:199], v[12:15]
	v_mfma_f32_16x16x32_bf16 v[4:7], v[144:147], v[204:207], v[4:7]
	v_mfma_f32_16x16x32_bf16 v[0:3], v[152:155], v[204:207], v[0:3]
	v_mfma_f32_16x16x32_bf16 v[52:55], v[148:151], v[184:187], v[52:55]
	v_mfma_f32_16x16x32_bf16 v[44:47], v[156:159], v[184:187], v[44:47]
	v_mfma_f32_16x16x32_bf16 v[36:39], v[148:151], v[192:195], v[36:39]
	v_mfma_f32_16x16x32_bf16 v[28:31], v[156:159], v[192:195], v[28:31]
	v_mfma_f32_16x16x32_bf16 v[20:23], v[148:151], v[200:203], v[20:23]
	v_mfma_f32_16x16x32_bf16 v[12:15], v[156:159], v[200:203], v[12:15]
	v_mfma_f32_16x16x32_bf16 v[4:7], v[148:151], v[208:211], v[4:7]
	v_mfma_f32_16x16x32_bf16 v[0:3], v[156:159], v[208:211], v[0:3]
	s_setprio 0
	s_barrier
	s_add_i32 s51, s51, 2
	s_cmp_gt_u32 s51, 13
	s_cbranch_scc1 .LBB0_726
	s_mov_b64 s[20:21], s[22:23]
	s_branch .LBB0_721

.Lpk2_LBB0_1250:
.Lpk2_LBB0_1251:
	s_add_u32 s24, s22, 0x100
	s_addc_u32 s25, s23, 0
	s_and_b64 s[70:71], s[26:27], exec
	s_cselect_b32 s6, 0, s24
	s_add_u32 s70, s53, s22
	s_addc_u32 s71, s56, s23
	s_and_b64 s[22:23], s[26:27], exec
	s_cselect_b32 s23, s17, s71
	s_cselect_b32 s22, s50, s70
	s_add_u32 s98, s4, s6
	s_addc_u32 s99, s5, s7
	s_mov_b32 m0, s29
	s_add_u32 s26, s22, 0x20000
	ds_read_b128 v[180:183], v179 offset:16384
	ds_read_b128 v[184:187], v179 offset:17408
	ds_read_b128 v[188:191], v179 offset:18432
	ds_read_b128 v[192:195], v179 offset:19456
	ds_read_b128 v[196:199], v179 offset:20480
	ds_read_b128 v[200:203], v179 offset:21504
	ds_read_b128 v[204:207], v179 offset:22528
	ds_read_b128 v[208:211], v179 offset:23552
	global_load_lds_dwordx4 v162, s[22:23]
	s_mov_b32 m0, s30
	s_addc_u32 s27, s23, 0
	global_load_lds_dwordx4 v160, s[22:23]
	s_mov_b32 m0, s31
	s_nop 0
	global_load_lds_dwordx4 v162, s[26:27]
	s_mov_b32 m0, s34
	s_nop 0
	global_load_lds_dwordx4 v160, s[26:27]
	s_waitcnt vmcnt(6)
	s_waitcnt lgkmcnt(0)
	s_barrier
	s_setprio 1
	s_waitcnt lgkmcnt(0)
	v_mfma_f32_16x16x128_f8f6f4 v[92:95], v[16:23], v[180:187], 0
	v_mfma_f32_16x16x128_f8f6f4 v[88:91], v[24:31], v[180:187], 0
	v_mfma_f32_16x16x128_f8f6f4 v[76:79], v[16:23], v[188:195], 0
	v_mfma_f32_16x16x128_f8f6f4 v[72:75], v[24:31], v[188:195], 0
	v_mfma_f32_16x16x128_f8f6f4 v[212:215], v[16:23], v[196:203], 0
	v_mfma_f32_16x16x128_f8f6f4 v[216:219], v[24:31], v[196:203], 0
	v_mfma_f32_16x16x128_f8f6f4 v[220:223], v[16:23], v[204:211], 0
	v_mfma_f32_16x16x128_f8f6f4 v[224:227], v[24:31], v[204:211], 0
	v_mfma_f32_16x16x128_f8f6f4 v[84:87], v[0:7], v[180:187], 0
	v_mfma_f32_16x16x128_f8f6f4 v[80:83], v[8:15], v[180:187], 0
	v_mfma_f32_16x16x128_f8f6f4 v[68:71], v[0:7], v[188:195], 0
	v_mfma_f32_16x16x128_f8f6f4 v[64:67], v[8:15], v[188:195], 0
	v_mfma_f32_16x16x128_f8f6f4 v[228:231], v[0:7], v[196:203], 0
	v_mfma_f32_16x16x128_f8f6f4 v[196:199], v[8:15], v[196:203], 0
	v_mfma_f32_16x16x128_f8f6f4 v[200:203], v[0:7], v[204:211], 0
	v_mfma_f32_16x16x128_f8f6f4 v[204:207], v[8:15], v[204:211], 0
	s_setprio 0
	s_barrier
	s_add_i32 s26, 0, 0x18000
	s_add_i32 s27, 0, 0x1c000
	v_add_u32_e32 v12, s26, v176
	v_add_u32_e32 v28, s27, v176
	ds_read_b128 v[0:3], v12
	ds_read_b128 v[4:7], v12 offset:1024
	ds_read_b128 v[8:11], v12 offset:2048
	ds_read_b128 v[12:15], v12 offset:3072
	ds_read_b128 v[16:19], v28
	ds_read_b128 v[20:23], v28 offset:1024
	ds_read_b128 v[24:27], v28 offset:2048
	ds_read_b128 v[28:31], v28 offset:3072
	s_mov_b32 m0, s36
	ds_read_b128 v[32:35], v179 offset:32768
	ds_read_b128 v[36:39], v179 offset:33792
	ds_read_b128 v[40:43], v179 offset:34816
	ds_read_b128 v[44:47], v179 offset:35840
	ds_read_b128 v[48:51], v179 offset:36864
	ds_read_b128 v[52:55], v179 offset:37888
	ds_read_b128 v[56:59], v179 offset:38912
	ds_read_b128 v[60:63], v179 offset:39936
	global_load_lds_dwordx4 v168, s[98:99]
	s_mov_b32 m0, s37
	s_nop 0
	global_load_lds_dwordx4 v166, s[98:99]
	s_mov_b32 m0, s28
	s_nop 0
	global_load_lds_dwordx4 v164, s[98:99]
	s_mov_b32 m0, s35
	s_nop 0
	global_load_lds_dwordx4 v170, s[98:99]
	s_waitcnt vmcnt(8)
	s_waitcnt lgkmcnt(0)
	s_barrier
	s_setprio 1
	s_waitcnt lgkmcnt(0)
	v_mfma_f32_16x16x128_f8f6f4 v[156:159], v[0:7], v[32:39], v[156:159]
	v_mfma_f32_16x16x128_f8f6f4 v[152:155], v[8:15], v[32:39], v[152:155]
	v_mfma_f32_16x16x128_f8f6f4 v[140:143], v[0:7], v[40:47], v[140:143]
	v_mfma_f32_16x16x128_f8f6f4 v[136:139], v[8:15], v[40:47], v[136:139]
	v_mfma_f32_16x16x128_f8f6f4 v[124:127], v[0:7], v[48:55], v[124:127]
	v_mfma_f32_16x16x128_f8f6f4 v[120:123], v[8:15], v[48:55], v[120:123]
	v_mfma_f32_16x16x128_f8f6f4 v[108:111], v[0:7], v[56:63], v[108:111]
	v_mfma_f32_16x16x128_f8f6f4 v[104:107], v[8:15], v[56:63], v[104:107]
	v_mfma_f32_16x16x128_f8f6f4 v[148:151], v[16:23], v[32:39], v[148:151]
	v_mfma_f32_16x16x128_f8f6f4 v[144:147], v[24:31], v[32:39], v[144:147]
	v_mfma_f32_16x16x128_f8f6f4 v[132:135], v[16:23], v[40:47], v[132:135]
	v_mfma_f32_16x16x128_f8f6f4 v[128:131], v[24:31], v[40:47], v[128:131]
	v_mfma_f32_16x16x128_f8f6f4 v[116:119], v[16:23], v[48:55], v[116:119]
	v_mfma_f32_16x16x128_f8f6f4 v[112:115], v[24:31], v[48:55], v[112:115]
	v_mfma_f32_16x16x128_f8f6f4 v[100:103], v[16:23], v[56:63], v[100:103]
	v_mfma_f32_16x16x128_f8f6f4 v[96:99], v[24:31], v[56:63], v[96:99]
	s_setprio 0
	s_barrier
	s_add_i32 s6, s26, s84
	s_add_u32 s100, s22, s10
	s_addc_u32 s101, s23, s11
	s_add_u32 s98, s98, s10
	s_addc_u32 s99, s99, s11
	s_mov_b32 m0, s6
	ds_read_b128 v[32:35], v179 offset:49152
	ds_read_b128 v[36:39], v179 offset:50176
	ds_read_b128 v[48:51], v179 offset:51200
	ds_read_b128 v[52:55], v179 offset:52224
	ds_read_b128 v[180:183], v179 offset:53248
	ds_read_b128 v[184:187], v179 offset:54272
	ds_read_b128 v[188:191], v179 offset:55296
	ds_read_b128 v[192:195], v179 offset:56320
	global_load_lds_dwordx4 v162, s[100:101]
	s_add_i32 m0, s6, 0x2000
	s_add_u32 s22, s22, 0x20080
	s_addc_u32 s23, s23, 0
	s_add_i32 s6, s27, s84
	global_load_lds_dwordx4 v160, s[100:101]
	s_mov_b32 m0, s6
	s_nop 0
	global_load_lds_dwordx4 v162, s[22:23]
	s_add_i32 m0, s6, 0x2000
	s_nop 0
	global_load_lds_dwordx4 v160, s[22:23]
	s_mov_b32 m0, s38
	s_nop 0
	global_load_lds_dwordx4 v164, s[98:99]
	s_mov_b32 m0, s39
	s_nop 0
	global_load_lds_dwordx4 v170, s[98:99]
	s_waitcnt vmcnt(6)
	s_waitcnt lgkmcnt(0)
	s_barrier
	s_setprio 1
	s_waitcnt lgkmcnt(0)
	v_mfma_f32_16x16x128_f8f6f4 v[92:95], v[0:7], v[32:39], v[92:95]
	v_mfma_f32_16x16x128_f8f6f4 v[88:91], v[8:15], v[32:39], v[88:91]
	v_mfma_f32_16x16x128_f8f6f4 v[76:79], v[0:7], v[48:55], v[76:79]
	v_mfma_f32_16x16x128_f8f6f4 v[72:75], v[8:15], v[48:55], v[72:75]
	v_mfma_f32_16x16x128_f8f6f4 v[60:63], v[0:7], v[180:187], v[212:215]
	v_mfma_f32_16x16x128_f8f6f4 v[56:59], v[8:15], v[180:187], v[216:219]
	v_mfma_f32_16x16x128_f8f6f4 v[44:47], v[0:7], v[188:195], v[220:223]
	v_mfma_f32_16x16x128_f8f6f4 v[40:43], v[8:15], v[188:195], v[224:227]
	v_mfma_f32_16x16x128_f8f6f4 v[84:87], v[16:23], v[32:39], v[84:87]
	v_mfma_f32_16x16x128_f8f6f4 v[80:83], v[24:31], v[32:39], v[80:83]
	v_mfma_f32_16x16x128_f8f6f4 v[68:71], v[16:23], v[48:55], v[68:71]
	v_mfma_f32_16x16x128_f8f6f4 v[64:67], v[24:31], v[48:55], v[64:67]
	v_mfma_f32_16x16x128_f8f6f4 v[52:55], v[16:23], v[180:187], v[228:231]
	v_mfma_f32_16x16x128_f8f6f4 v[48:51], v[24:31], v[180:187], v[196:199]
	v_mfma_f32_16x16x128_f8f6f4 v[36:39], v[16:23], v[188:195], v[200:203]
	v_mfma_f32_16x16x128_f8f6f4 v[32:35], v[24:31], v[188:195], v[204:207]
	s_setprio 0
	s_barrier
	s_add_i32 s57, s57, 2
	s_cmp_gt_u32 s57, 5
	s_cbranch_scc1 .LBB0_1253
	s_mov_b64 s[22:23], s[24:25]
	s_branch .LBB0_1248

.LBB0_1250:
.LBB0_1251:
	s_add_u32 s24, s22, 0x100
	s_addc_u32 s25, s23, 0
	s_and_b64 s[70:71], s[26:27], exec
	s_cselect_b32 s6, 0, s24
	s_add_u32 s70, s53, s22
	s_addc_u32 s71, s56, s23
	s_and_b64 s[22:23], s[26:27], exec
	s_cselect_b32 s23, s17, s71
	s_cselect_b32 s22, s50, s70
	s_add_u32 s98, s4, s6
	s_addc_u32 s99, s5, s7
	s_mov_b32 m0, s29
	s_add_u32 s26, s22, 0x20000
	ds_read_b128 v[180:183], v179 offset:16384
	ds_read_b128 v[184:187], v179 offset:17408
	ds_read_b128 v[188:191], v179 offset:18432
	ds_read_b128 v[192:195], v179 offset:19456
	ds_read_b128 v[196:199], v179 offset:20480
	ds_read_b128 v[200:203], v179 offset:21504
	ds_read_b128 v[204:207], v179 offset:22528
	ds_read_b128 v[208:211], v179 offset:23552
	global_load_lds_dwordx4 v162, s[22:23]
	s_mov_b32 m0, s30
	s_addc_u32 s27, s23, 0
	global_load_lds_dwordx4 v160, s[22:23]
	s_mov_b32 m0, s31
	s_nop 0
	global_load_lds_dwordx4 v162, s[26:27]
	s_mov_b32 m0, s34
	s_nop 0
	global_load_lds_dwordx4 v160, s[26:27]
	s_waitcnt vmcnt(6)
	s_waitcnt lgkmcnt(0)
	s_barrier
	s_setprio 1
	s_waitcnt lgkmcnt(0)
	v_mfma_f32_16x16x128_f8f6f4 v[92:95], v[16:23], v[180:187], v[92:95]
	v_mfma_f32_16x16x128_f8f6f4 v[88:91], v[24:31], v[180:187], v[88:91]
	v_mfma_f32_16x16x128_f8f6f4 v[76:79], v[16:23], v[188:195], v[76:79]
	v_mfma_f32_16x16x128_f8f6f4 v[72:75], v[24:31], v[188:195], v[72:75]
	v_mfma_f32_16x16x128_f8f6f4 v[212:215], v[16:23], v[196:203], v[60:63]
	v_mfma_f32_16x16x128_f8f6f4 v[216:219], v[24:31], v[196:203], v[56:59]
	v_mfma_f32_16x16x128_f8f6f4 v[220:223], v[16:23], v[204:211], v[44:47]
	v_mfma_f32_16x16x128_f8f6f4 v[224:227], v[24:31], v[204:211], v[40:43]
	v_mfma_f32_16x16x128_f8f6f4 v[84:87], v[0:7], v[180:187], v[84:87]
	v_mfma_f32_16x16x128_f8f6f4 v[80:83], v[8:15], v[180:187], v[80:83]
	v_mfma_f32_16x16x128_f8f6f4 v[68:71], v[0:7], v[188:195], v[68:71]
	v_mfma_f32_16x16x128_f8f6f4 v[64:67], v[8:15], v[188:195], v[64:67]
	v_mfma_f32_16x16x128_f8f6f4 v[228:231], v[0:7], v[196:203], v[52:55]
	v_mfma_f32_16x16x128_f8f6f4 v[196:199], v[8:15], v[196:203], v[48:51]
	v_mfma_f32_16x16x128_f8f6f4 v[200:203], v[0:7], v[204:211], v[36:39]
	v_mfma_f32_16x16x128_f8f6f4 v[204:207], v[8:15], v[204:211], v[32:35]
	s_setprio 0
	s_barrier
	s_add_i32 s26, 0, 0x18000
	s_add_i32 s27, 0, 0x1c000
	v_add_u32_e32 v12, s26, v176
	v_add_u32_e32 v28, s27, v176
	ds_read_b128 v[0:3], v12
	ds_read_b128 v[4:7], v12 offset:1024
	ds_read_b128 v[8:11], v12 offset:2048
	ds_read_b128 v[12:15], v12 offset:3072
	ds_read_b128 v[16:19], v28
	ds_read_b128 v[20:23], v28 offset:1024
	ds_read_b128 v[24:27], v28 offset:2048
	ds_read_b128 v[28:31], v28 offset:3072
	s_mov_b32 m0, s36
	ds_read_b128 v[32:35], v179 offset:32768
	ds_read_b128 v[36:39], v179 offset:33792
	ds_read_b128 v[40:43], v179 offset:34816
	ds_read_b128 v[44:47], v179 offset:35840
	ds_read_b128 v[48:51], v179 offset:36864
	ds_read_b128 v[52:55], v179 offset:37888
	ds_read_b128 v[56:59], v179 offset:38912
	ds_read_b128 v[60:63], v179 offset:39936
	global_load_lds_dwordx4 v168, s[98:99]
	s_mov_b32 m0, s37
	s_nop 0
	global_load_lds_dwordx4 v166, s[98:99]
	s_mov_b32 m0, s28
	s_nop 0
	global_load_lds_dwordx4 v164, s[98:99]
	s_mov_b32 m0, s35
	s_nop 0
	global_load_lds_dwordx4 v170, s[98:99]
	s_waitcnt vmcnt(8)
	s_waitcnt lgkmcnt(0)
	s_barrier
	s_setprio 1
	s_waitcnt lgkmcnt(0)
	v_mfma_f32_16x16x128_f8f6f4 v[156:159], v[0:7], v[32:39], v[156:159]
	v_mfma_f32_16x16x128_f8f6f4 v[152:155], v[8:15], v[32:39], v[152:155]
	v_mfma_f32_16x16x128_f8f6f4 v[140:143], v[0:7], v[40:47], v[140:143]
	v_mfma_f32_16x16x128_f8f6f4 v[136:139], v[8:15], v[40:47], v[136:139]
	v_mfma_f32_16x16x128_f8f6f4 v[124:127], v[0:7], v[48:55], v[124:127]
	v_mfma_f32_16x16x128_f8f6f4 v[120:123], v[8:15], v[48:55], v[120:123]
	v_mfma_f32_16x16x128_f8f6f4 v[108:111], v[0:7], v[56:63], v[108:111]
	v_mfma_f32_16x16x128_f8f6f4 v[104:107], v[8:15], v[56:63], v[104:107]
	v_mfma_f32_16x16x128_f8f6f4 v[148:151], v[16:23], v[32:39], v[148:151]
	v_mfma_f32_16x16x128_f8f6f4 v[144:147], v[24:31], v[32:39], v[144:147]
	v_mfma_f32_16x16x128_f8f6f4 v[132:135], v[16:23], v[40:47], v[132:135]
	v_mfma_f32_16x16x128_f8f6f4 v[128:131], v[24:31], v[40:47], v[128:131]
	v_mfma_f32_16x16x128_f8f6f4 v[116:119], v[16:23], v[48:55], v[116:119]
	v_mfma_f32_16x16x128_f8f6f4 v[112:115], v[24:31], v[48:55], v[112:115]
	v_mfma_f32_16x16x128_f8f6f4 v[100:103], v[16:23], v[56:63], v[100:103]
	v_mfma_f32_16x16x128_f8f6f4 v[96:99], v[24:31], v[56:63], v[96:99]
	s_setprio 0
	s_barrier
	s_add_i32 s6, s26, s84
	s_add_u32 s100, s22, s10
	s_addc_u32 s101, s23, s11
	s_add_u32 s98, s98, s10
	s_addc_u32 s99, s99, s11
	s_mov_b32 m0, s6
	ds_read_b128 v[32:35], v179 offset:49152
	ds_read_b128 v[36:39], v179 offset:50176
	ds_read_b128 v[48:51], v179 offset:51200
	ds_read_b128 v[52:55], v179 offset:52224
	ds_read_b128 v[180:183], v179 offset:53248
	ds_read_b128 v[184:187], v179 offset:54272
	ds_read_b128 v[188:191], v179 offset:55296
	ds_read_b128 v[192:195], v179 offset:56320
	global_load_lds_dwordx4 v162, s[100:101]
	s_add_i32 m0, s6, 0x2000
	s_add_u32 s22, s22, 0x20080
	s_addc_u32 s23, s23, 0
	s_add_i32 s6, s27, s84
	global_load_lds_dwordx4 v160, s[100:101]
	s_mov_b32 m0, s6
	s_nop 0
	global_load_lds_dwordx4 v162, s[22:23]
	s_add_i32 m0, s6, 0x2000
	s_nop 0
	global_load_lds_dwordx4 v160, s[22:23]
	s_mov_b32 m0, s38
	s_nop 0
	global_load_lds_dwordx4 v164, s[98:99]
	s_mov_b32 m0, s39
	s_nop 0
	global_load_lds_dwordx4 v170, s[98:99]
	s_waitcnt vmcnt(6)
	s_waitcnt lgkmcnt(0)
	s_barrier
	s_setprio 1
	s_waitcnt lgkmcnt(0)
	v_mfma_f32_16x16x128_f8f6f4 v[92:95], v[0:7], v[32:39], v[92:95]
	v_mfma_f32_16x16x128_f8f6f4 v[88:91], v[8:15], v[32:39], v[88:91]
	v_mfma_f32_16x16x128_f8f6f4 v[76:79], v[0:7], v[48:55], v[76:79]
	v_mfma_f32_16x16x128_f8f6f4 v[72:75], v[8:15], v[48:55], v[72:75]
	v_mfma_f32_16x16x128_f8f6f4 v[60:63], v[0:7], v[180:187], v[212:215]
	v_mfma_f32_16x16x128_f8f6f4 v[56:59], v[8:15], v[180:187], v[216:219]
	v_mfma_f32_16x16x128_f8f6f4 v[44:47], v[0:7], v[188:195], v[220:223]
	v_mfma_f32_16x16x128_f8f6f4 v[40:43], v[8:15], v[188:195], v[224:227]
	v_mfma_f32_16x16x128_f8f6f4 v[84:87], v[16:23], v[32:39], v[84:87]
	v_mfma_f32_16x16x128_f8f6f4 v[80:83], v[24:31], v[32:39], v[80:83]
	v_mfma_f32_16x16x128_f8f6f4 v[68:71], v[16:23], v[48:55], v[68:71]
	v_mfma_f32_16x16x128_f8f6f4 v[64:67], v[24:31], v[48:55], v[64:67]
	v_mfma_f32_16x16x128_f8f6f4 v[52:55], v[16:23], v[180:187], v[228:231]
	v_mfma_f32_16x16x128_f8f6f4 v[48:51], v[24:31], v[180:187], v[196:199]
	v_mfma_f32_16x16x128_f8f6f4 v[36:39], v[16:23], v[188:195], v[200:203]
	v_mfma_f32_16x16x128_f8f6f4 v[32:35], v[24:31], v[188:195], v[204:207]
	s_setprio 0
	s_barrier
	s_add_i32 s57, s57, 2
	s_cmp_gt_u32 s57, 5
	s_cbranch_scc1 .LBB0_1253
	s_mov_b64 s[22:23], s[24:25]
	s_branch .LBB0_1248

.Lpk3_LBB0_1326:
.Lpk3_LBB0_1327:
	s_add_u32 s20, s18, 0x100
	s_addc_u32 s21, s19, 0
	s_and_b64 s[56:57], s[22:23], exec
	s_cselect_b32 s4, 0, s20
	s_add_u32 s53, s50, s18
	s_addc_u32 s56, s51, s19
	s_and_b64 s[18:19], s[22:23], exec
	s_cselect_b32 s19, s15, s56
	s_cselect_b32 s18, s14, s53
	s_add_u32 s98, s2, s4
	s_addc_u32 s99, s3, s5
	s_mov_b32 m0, s26
	s_add_u32 s22, s18, 0x58000
	ds_read_b128 v[178:181], v177 offset:16384
	ds_read_b128 v[182:185], v177 offset:17408
	ds_read_b128 v[186:189], v177 offset:18432
	ds_read_b128 v[190:193], v177 offset:19456
	ds_read_b128 v[194:197], v177 offset:20480
	ds_read_b128 v[198:201], v177 offset:21504
	ds_read_b128 v[202:205], v177 offset:22528
	ds_read_b128 v[206:209], v177 offset:23552
	global_load_lds_dwordx4 v162, s[18:19]
	s_mov_b32 m0, s27
	s_addc_u32 s23, s19, 0
	global_load_lds_dwordx4 v160, s[18:19]
	s_mov_b32 m0, s29
	s_nop 0
	global_load_lds_dwordx4 v162, s[22:23]
	s_mov_b32 m0, s30
	s_nop 0
	global_load_lds_dwordx4 v160, s[22:23]
	s_waitcnt vmcnt(6)
	s_waitcnt lgkmcnt(0)
	s_barrier
	s_setprio 1
	s_waitcnt lgkmcnt(0)
	v_mfma_f32_16x16x128_f8f6f4 v[92:95], v[16:23], v[178:185], 0
	v_mfma_f32_16x16x128_f8f6f4 v[88:91], v[24:31], v[178:185], 0
	v_mfma_f32_16x16x128_f8f6f4 v[76:79], v[16:23], v[186:193], 0
	v_mfma_f32_16x16x128_f8f6f4 v[72:75], v[24:31], v[186:193], 0
	v_mfma_f32_16x16x128_f8f6f4 v[210:213], v[16:23], v[194:201], 0
	v_mfma_f32_16x16x128_f8f6f4 v[214:217], v[24:31], v[194:201], 0
	v_mfma_f32_16x16x128_f8f6f4 v[218:221], v[16:23], v[202:209], 0
	v_mfma_f32_16x16x128_f8f6f4 v[222:225], v[24:31], v[202:209], 0
	v_mfma_f32_16x16x128_f8f6f4 v[84:87], v[0:7], v[178:185], 0
	v_mfma_f32_16x16x128_f8f6f4 v[80:83], v[8:15], v[178:185], 0
	v_mfma_f32_16x16x128_f8f6f4 v[68:71], v[0:7], v[186:193], 0
	v_mfma_f32_16x16x128_f8f6f4 v[64:67], v[8:15], v[186:193], 0
	v_mfma_f32_16x16x128_f8f6f4 v[226:229], v[0:7], v[194:201], 0
	v_mfma_f32_16x16x128_f8f6f4 v[194:197], v[8:15], v[194:201], 0
	v_mfma_f32_16x16x128_f8f6f4 v[198:201], v[0:7], v[202:209], 0
	v_mfma_f32_16x16x128_f8f6f4 v[202:205], v[8:15], v[202:209], 0
	s_setprio 0
	s_barrier
	s_add_i32 s22, 0, 0x18000
	s_add_i32 s23, 0, 0x1c000
	v_add_u32_e32 v12, s22, v173
	v_add_u32_e32 v28, s23, v173
	ds_read_b128 v[0:3], v12
	ds_read_b128 v[4:7], v12 offset:1024
	ds_read_b128 v[8:11], v12 offset:2048
	ds_read_b128 v[12:15], v12 offset:3072
	ds_read_b128 v[16:19], v28
	ds_read_b128 v[20:23], v28 offset:1024
	ds_read_b128 v[24:27], v28 offset:2048
	ds_read_b128 v[28:31], v28 offset:3072
	s_mov_b32 m0, s34
	ds_read_b128 v[32:35], v177 offset:32768
	ds_read_b128 v[36:39], v177 offset:33792
	ds_read_b128 v[40:43], v177 offset:34816
	ds_read_b128 v[44:47], v177 offset:35840
	ds_read_b128 v[48:51], v177 offset:36864
	ds_read_b128 v[52:55], v177 offset:37888
	ds_read_b128 v[56:59], v177 offset:38912
	ds_read_b128 v[60:63], v177 offset:39936
	global_load_lds_dwordx4 v166, s[98:99]
	s_mov_b32 m0, s35
	s_nop 0
	global_load_lds_dwordx4 v170, s[98:99]
	s_mov_b32 m0, s25
	s_nop 0
	global_load_lds_dwordx4 v164, s[98:99]
	s_mov_b32 m0, s31
	s_nop 0
	global_load_lds_dwordx4 v168, s[98:99]
	s_waitcnt vmcnt(8)
	s_waitcnt lgkmcnt(0)
	s_barrier
	s_setprio 1
	s_waitcnt lgkmcnt(0)
	v_mfma_f32_16x16x128_f8f6f4 v[156:159], v[0:7], v[32:39], v[156:159]
	v_mfma_f32_16x16x128_f8f6f4 v[152:155], v[8:15], v[32:39], v[152:155]
	v_mfma_f32_16x16x128_f8f6f4 v[140:143], v[0:7], v[40:47], v[140:143]
	v_mfma_f32_16x16x128_f8f6f4 v[136:139], v[8:15], v[40:47], v[136:139]
	v_mfma_f32_16x16x128_f8f6f4 v[124:127], v[0:7], v[48:55], v[124:127]
	v_mfma_f32_16x16x128_f8f6f4 v[120:123], v[8:15], v[48:55], v[120:123]
	v_mfma_f32_16x16x128_f8f6f4 v[108:111], v[0:7], v[56:63], v[108:111]
	v_mfma_f32_16x16x128_f8f6f4 v[104:107], v[8:15], v[56:63], v[104:107]
	v_mfma_f32_16x16x128_f8f6f4 v[148:151], v[16:23], v[32:39], v[148:151]
	v_mfma_f32_16x16x128_f8f6f4 v[144:147], v[24:31], v[32:39], v[144:147]
	v_mfma_f32_16x16x128_f8f6f4 v[132:135], v[16:23], v[40:47], v[132:135]
	v_mfma_f32_16x16x128_f8f6f4 v[128:131], v[24:31], v[40:47], v[128:131]
	v_mfma_f32_16x16x128_f8f6f4 v[116:119], v[16:23], v[48:55], v[116:119]
	v_mfma_f32_16x16x128_f8f6f4 v[112:115], v[24:31], v[48:55], v[112:115]
	v_mfma_f32_16x16x128_f8f6f4 v[100:103], v[16:23], v[56:63], v[100:103]
	v_mfma_f32_16x16x128_f8f6f4 v[96:99], v[24:31], v[56:63], v[96:99]
	s_setprio 0
	s_barrier
	s_add_i32 s4, s22, s84
	s_add_u32 s100, s18, s10
	s_addc_u32 s101, s19, s11
	s_add_u32 s98, s98, s10
	s_addc_u32 s99, s99, s11
	s_mov_b32 m0, s4
	ds_read_b128 v[32:35], v177 offset:49152
	ds_read_b128 v[36:39], v177 offset:50176
	ds_read_b128 v[48:51], v177 offset:51200
	ds_read_b128 v[52:55], v177 offset:52224
	ds_read_b128 v[178:181], v177 offset:53248
	ds_read_b128 v[182:185], v177 offset:54272
	ds_read_b128 v[186:189], v177 offset:55296
	ds_read_b128 v[190:193], v177 offset:56320
	global_load_lds_dwordx4 v162, s[100:101]
	s_add_i32 m0, s4, 0x2000
	s_add_u32 s18, s18, 0x58080
	s_addc_u32 s19, s19, 0
	s_add_i32 s4, s23, s84
	global_load_lds_dwordx4 v160, s[100:101]
	s_mov_b32 m0, s4
	s_nop 0
	global_load_lds_dwordx4 v162, s[18:19]
	s_add_i32 m0, s4, 0x2000
	s_nop 0
	global_load_lds_dwordx4 v160, s[18:19]
	s_mov_b32 m0, s36
	s_nop 0
	global_load_lds_dwordx4 v164, s[98:99]
	s_mov_b32 m0, s37
	s_nop 0
	global_load_lds_dwordx4 v168, s[98:99]
	s_waitcnt vmcnt(6)
	s_waitcnt lgkmcnt(0)
	s_barrier
	s_setprio 1
	s_waitcnt lgkmcnt(0)
	v_mfma_f32_16x16x128_f8f6f4 v[92:95], v[0:7], v[32:39], v[92:95]
	v_mfma_f32_16x16x128_f8f6f4 v[88:91], v[8:15], v[32:39], v[88:91]
	v_mfma_f32_16x16x128_f8f6f4 v[76:79], v[0:7], v[48:55], v[76:79]
	v_mfma_f32_16x16x128_f8f6f4 v[72:75], v[8:15], v[48:55], v[72:75]
	v_mfma_f32_16x16x128_f8f6f4 v[60:63], v[0:7], v[178:185], v[210:213]
	v_mfma_f32_16x16x128_f8f6f4 v[56:59], v[8:15], v[178:185], v[214:217]
	v_mfma_f32_16x16x128_f8f6f4 v[44:47], v[0:7], v[186:193], v[218:221]
	v_mfma_f32_16x16x128_f8f6f4 v[40:43], v[8:15], v[186:193], v[222:225]
	v_mfma_f32_16x16x128_f8f6f4 v[84:87], v[16:23], v[32:39], v[84:87]
	v_mfma_f32_16x16x128_f8f6f4 v[80:83], v[24:31], v[32:39], v[80:83]
	v_mfma_f32_16x16x128_f8f6f4 v[68:71], v[16:23], v[48:55], v[68:71]
	v_mfma_f32_16x16x128_f8f6f4 v[64:67], v[24:31], v[48:55], v[64:67]
	v_mfma_f32_16x16x128_f8f6f4 v[52:55], v[16:23], v[178:185], v[226:229]
	v_mfma_f32_16x16x128_f8f6f4 v[48:51], v[24:31], v[178:185], v[194:197]
	v_mfma_f32_16x16x128_f8f6f4 v[36:39], v[16:23], v[186:193], v[198:201]
	v_mfma_f32_16x16x128_f8f6f4 v[32:35], v[24:31], v[186:193], v[202:205]
	s_setprio 0
	s_barrier
	s_add_i32 s52, s52, 2
	s_cmp_gt_u32 s52, 19
	s_cbranch_scc1 .LBB0_1329
	s_mov_b64 s[18:19], s[20:21]
	s_branch .LBB0_1324

.LBB0_1326:
.LBB0_1327:
	s_add_u32 s20, s18, 0x100
	s_addc_u32 s21, s19, 0
	s_and_b64 s[56:57], s[22:23], exec
	s_cselect_b32 s4, 0, s20
	s_add_u32 s53, s50, s18
	s_addc_u32 s56, s51, s19
	s_and_b64 s[18:19], s[22:23], exec
	s_cselect_b32 s19, s15, s56
	s_cselect_b32 s18, s14, s53
	s_add_u32 s98, s2, s4
	s_addc_u32 s99, s3, s5
	s_mov_b32 m0, s26
	s_add_u32 s22, s18, 0x58000
	ds_read_b128 v[178:181], v177 offset:16384
	ds_read_b128 v[182:185], v177 offset:17408
	ds_read_b128 v[186:189], v177 offset:18432
	ds_read_b128 v[190:193], v177 offset:19456
	ds_read_b128 v[194:197], v177 offset:20480
	ds_read_b128 v[198:201], v177 offset:21504
	ds_read_b128 v[202:205], v177 offset:22528
	ds_read_b128 v[206:209], v177 offset:23552
	global_load_lds_dwordx4 v162, s[18:19]
	s_mov_b32 m0, s27
	s_addc_u32 s23, s19, 0
	global_load_lds_dwordx4 v160, s[18:19]
	s_mov_b32 m0, s29
	s_nop 0
	global_load_lds_dwordx4 v162, s[22:23]
	s_mov_b32 m0, s30
	s_nop 0
	global_load_lds_dwordx4 v160, s[22:23]
	s_waitcnt vmcnt(6)
	s_waitcnt lgkmcnt(0)
	s_barrier
	s_setprio 1
	s_waitcnt lgkmcnt(0)
	v_mfma_f32_16x16x128_f8f6f4 v[92:95], v[16:23], v[178:185], v[92:95]
	v_mfma_f32_16x16x128_f8f6f4 v[88:91], v[24:31], v[178:185], v[88:91]
	v_mfma_f32_16x16x128_f8f6f4 v[76:79], v[16:23], v[186:193], v[76:79]
	v_mfma_f32_16x16x128_f8f6f4 v[72:75], v[24:31], v[186:193], v[72:75]
	v_mfma_f32_16x16x128_f8f6f4 v[210:213], v[16:23], v[194:201], v[60:63]
	v_mfma_f32_16x16x128_f8f6f4 v[214:217], v[24:31], v[194:201], v[56:59]
	v_mfma_f32_16x16x128_f8f6f4 v[218:221], v[16:23], v[202:209], v[44:47]
	v_mfma_f32_16x16x128_f8f6f4 v[222:225], v[24:31], v[202:209], v[40:43]
	v_mfma_f32_16x16x128_f8f6f4 v[84:87], v[0:7], v[178:185], v[84:87]
	v_mfma_f32_16x16x128_f8f6f4 v[80:83], v[8:15], v[178:185], v[80:83]
	v_mfma_f32_16x16x128_f8f6f4 v[68:71], v[0:7], v[186:193], v[68:71]
	v_mfma_f32_16x16x128_f8f6f4 v[64:67], v[8:15], v[186:193], v[64:67]
	v_mfma_f32_16x16x128_f8f6f4 v[226:229], v[0:7], v[194:201], v[52:55]
	v_mfma_f32_16x16x128_f8f6f4 v[194:197], v[8:15], v[194:201], v[48:51]
	v_mfma_f32_16x16x128_f8f6f4 v[198:201], v[0:7], v[202:209], v[36:39]
	v_mfma_f32_16x16x128_f8f6f4 v[202:205], v[8:15], v[202:209], v[32:35]
	s_setprio 0
	s_barrier
	s_add_i32 s22, 0, 0x18000
	s_add_i32 s23, 0, 0x1c000
	v_add_u32_e32 v12, s22, v173
	v_add_u32_e32 v28, s23, v173
	ds_read_b128 v[0:3], v12
	ds_read_b128 v[4:7], v12 offset:1024
	ds_read_b128 v[8:11], v12 offset:2048
	ds_read_b128 v[12:15], v12 offset:3072
	ds_read_b128 v[16:19], v28
	ds_read_b128 v[20:23], v28 offset:1024
	ds_read_b128 v[24:27], v28 offset:2048
	ds_read_b128 v[28:31], v28 offset:3072
	s_mov_b32 m0, s34
	ds_read_b128 v[32:35], v177 offset:32768
	ds_read_b128 v[36:39], v177 offset:33792
	ds_read_b128 v[40:43], v177 offset:34816
	ds_read_b128 v[44:47], v177 offset:35840
	ds_read_b128 v[48:51], v177 offset:36864
	ds_read_b128 v[52:55], v177 offset:37888
	ds_read_b128 v[56:59], v177 offset:38912
	ds_read_b128 v[60:63], v177 offset:39936
	global_load_lds_dwordx4 v166, s[98:99]
	s_mov_b32 m0, s35
	s_nop 0
	global_load_lds_dwordx4 v170, s[98:99]
	s_mov_b32 m0, s25
	s_nop 0
	global_load_lds_dwordx4 v164, s[98:99]
	s_mov_b32 m0, s31
	s_nop 0
	global_load_lds_dwordx4 v168, s[98:99]
	s_waitcnt vmcnt(8)
	s_waitcnt lgkmcnt(0)
	s_barrier
	s_setprio 1
	s_waitcnt lgkmcnt(0)
	v_mfma_f32_16x16x128_f8f6f4 v[156:159], v[0:7], v[32:39], v[156:159]
	v_mfma_f32_16x16x128_f8f6f4 v[152:155], v[8:15], v[32:39], v[152:155]
	v_mfma_f32_16x16x128_f8f6f4 v[140:143], v[0:7], v[40:47], v[140:143]
	v_mfma_f32_16x16x128_f8f6f4 v[136:139], v[8:15], v[40:47], v[136:139]
	v_mfma_f32_16x16x128_f8f6f4 v[124:127], v[0:7], v[48:55], v[124:127]
	v_mfma_f32_16x16x128_f8f6f4 v[120:123], v[8:15], v[48:55], v[120:123]
	v_mfma_f32_16x16x128_f8f6f4 v[108:111], v[0:7], v[56:63], v[108:111]
	v_mfma_f32_16x16x128_f8f6f4 v[104:107], v[8:15], v[56:63], v[104:107]
	v_mfma_f32_16x16x128_f8f6f4 v[148:151], v[16:23], v[32:39], v[148:151]
	v_mfma_f32_16x16x128_f8f6f4 v[144:147], v[24:31], v[32:39], v[144:147]
	v_mfma_f32_16x16x128_f8f6f4 v[132:135], v[16:23], v[40:47], v[132:135]
	v_mfma_f32_16x16x128_f8f6f4 v[128:131], v[24:31], v[40:47], v[128:131]
	v_mfma_f32_16x16x128_f8f6f4 v[116:119], v[16:23], v[48:55], v[116:119]
	v_mfma_f32_16x16x128_f8f6f4 v[112:115], v[24:31], v[48:55], v[112:115]
	v_mfma_f32_16x16x128_f8f6f4 v[100:103], v[16:23], v[56:63], v[100:103]
	v_mfma_f32_16x16x128_f8f6f4 v[96:99], v[24:31], v[56:63], v[96:99]
	s_setprio 0
	s_barrier
	s_add_i32 s4, s22, s84
	s_add_u32 s100, s18, s10
	s_addc_u32 s101, s19, s11
	s_add_u32 s98, s98, s10
	s_addc_u32 s99, s99, s11
	s_mov_b32 m0, s4
	ds_read_b128 v[32:35], v177 offset:49152
	ds_read_b128 v[36:39], v177 offset:50176
	ds_read_b128 v[48:51], v177 offset:51200
	ds_read_b128 v[52:55], v177 offset:52224
	ds_read_b128 v[178:181], v177 offset:53248
	ds_read_b128 v[182:185], v177 offset:54272
	ds_read_b128 v[186:189], v177 offset:55296
	ds_read_b128 v[190:193], v177 offset:56320
	global_load_lds_dwordx4 v162, s[100:101]
	s_add_i32 m0, s4, 0x2000
	s_add_u32 s18, s18, 0x58080
	s_addc_u32 s19, s19, 0
	s_add_i32 s4, s23, s84
	global_load_lds_dwordx4 v160, s[100:101]
	s_mov_b32 m0, s4
	s_nop 0
	global_load_lds_dwordx4 v162, s[18:19]
	s_add_i32 m0, s4, 0x2000
	s_nop 0
	global_load_lds_dwordx4 v160, s[18:19]
	s_mov_b32 m0, s36
	s_nop 0
	global_load_lds_dwordx4 v164, s[98:99]
	s_mov_b32 m0, s37
	s_nop 0
	global_load_lds_dwordx4 v168, s[98:99]
	s_waitcnt vmcnt(6)
	s_waitcnt lgkmcnt(0)
	s_barrier
	s_setprio 1
	s_waitcnt lgkmcnt(0)
	v_mfma_f32_16x16x128_f8f6f4 v[92:95], v[0:7], v[32:39], v[92:95]
	v_mfma_f32_16x16x128_f8f6f4 v[88:91], v[8:15], v[32:39], v[88:91]
	v_mfma_f32_16x16x128_f8f6f4 v[76:79], v[0:7], v[48:55], v[76:79]
	v_mfma_f32_16x16x128_f8f6f4 v[72:75], v[8:15], v[48:55], v[72:75]
	v_mfma_f32_16x16x128_f8f6f4 v[60:63], v[0:7], v[178:185], v[210:213]
	v_mfma_f32_16x16x128_f8f6f4 v[56:59], v[8:15], v[178:185], v[214:217]
	v_mfma_f32_16x16x128_f8f6f4 v[44:47], v[0:7], v[186:193], v[218:221]
	v_mfma_f32_16x16x128_f8f6f4 v[40:43], v[8:15], v[186:193], v[222:225]
	v_mfma_f32_16x16x128_f8f6f4 v[84:87], v[16:23], v[32:39], v[84:87]
	v_mfma_f32_16x16x128_f8f6f4 v[80:83], v[24:31], v[32:39], v[80:83]
	v_mfma_f32_16x16x128_f8f6f4 v[68:71], v[16:23], v[48:55], v[68:71]
	v_mfma_f32_16x16x128_f8f6f4 v[64:67], v[24:31], v[48:55], v[64:67]
	v_mfma_f32_16x16x128_f8f6f4 v[52:55], v[16:23], v[178:185], v[226:229]
	v_mfma_f32_16x16x128_f8f6f4 v[48:51], v[24:31], v[178:185], v[194:197]
	v_mfma_f32_16x16x128_f8f6f4 v[36:39], v[16:23], v[186:193], v[198:201]
	v_mfma_f32_16x16x128_f8f6f4 v[32:35], v[24:31], v[186:193], v[202:205]
	s_setprio 0
	s_barrier
	s_add_i32 s52, s52, 2
	s_cmp_gt_u32 s52, 19
	s_cbranch_scc1 .LBB0_1329
	s_mov_b64 s[18:19], s[20:21]
	s_branch .LBB0_1324
